# v24: v22 + write-through (sc1) stores for cross-attention output and pool-mixer output
# baseline (speedup 1.0000x reference)
; template <int W> __device__ __forceinline__ void pool_item(const bf16* xa, bf16* ya, int m0, int cgi) {
;     const int t0 = m0 & (SEQ - 1); v4u rw[W + 7];
; #pragma unroll
;     for (int a = 0; a < W + 7; ++a) { const int tl = a - (W - 1); rw[a] = (t0 + tl >= 0) ? *(const v4u*)(xa + (size_t)(m0 + tl) * 512 + 8 * cgi) : (v4u){0u, 0u, 0u, 0u}; }
;     float s[8];
; #pragma unroll
;     for (int i = 0; i < 8; ++i) s[i] = 0.f;
; #pragma unroll
;     for (int a = 0; a < W - 1; ++a) { float xf[8]; unpk8(rw[a], xf);
; #pragma unroll
;         for (int i = 0; i < 8; ++i) s[i] += xf[i]; }
; #pragma unroll
;     for (int o = 0; o < 8; ++o) { float cur[8]; unpk8(rw[o + W - 1], cur);
; #pragma unroll
;         for (int i = 0; i < 8; ++i) s[i] += cur[i];
.LBB0_741:
	s_or_b64 exec, exec, s[16:17]
	v_ashrrev_i32_e32 v5, 31, v4
	v_or_b32_e32 v6, 1, v4
	v_lshlrev_b64 v[126:127], 10, v[4:5]
	v_ashrrev_i32_e32 v7, 31, v6
	v_lshlrev_b32_e32 v64, 3, v2
	v_lshl_add_u64 v[2:3], v[0:1], 0, v[126:127]
	v_lshlrev_b64 v[116:117], 10, v[6:7]
	v_lshl_add_u64 v[6:7], v[0:1], 0, v[116:117]
	global_load_dwordx4 v[90:93], v[2:3], off
	global_load_dwordx4 v[66:69], v[6:7], off
	s_waitcnt vmcnt(2)
	v_lshlrev_b32_e32 v133, 16, v37
	v_lshlrev_b32_e32 v132, 16, v36
	v_pk_add_f32 v[106:107], v[132:133], 0 op_sel_hi:[1,0]
	v_lshlrev_b32_e32 v123, 16, v29
	v_lshlrev_b32_e32 v122, 16, v28
	v_and_b32_e32 v125, 0xffff0000, v29
	v_and_b32_e32 v124, 0xffff0000, v28
	v_lshlrev_b32_e32 v114, 16, v48
	v_lshlrev_b32_e32 v115, 16, v49
	v_pk_add_f32 v[28:29], v[106:107], v[122:123]
	v_lshlrev_b32_e32 v110, 16, v50
	v_and_b32_e32 v108, 0xffff0000, v50
	v_lshlrev_b32_e32 v111, 16, v51
	v_and_b32_e32 v109, 0xffff0000, v51
	v_pk_add_f32 v[28:29], v[28:29], v[114:115]
	v_lshlrev_b32_e32 v51, 16, v13
	v_lshlrev_b32_e32 v50, 16, v12
	v_and_b32_e32 v135, 0xffff0000, v37
	v_and_b32_e32 v134, 0xffff0000, v36
	v_pk_add_f32 v[28:29], v[28:29], v[50:51]
	v_lshlrev_b32_e32 v37, 16, v25
	v_lshlrev_b32_e32 v36, 16, v24
	v_lshlrev_b32_e32 v119, 16, v31
	v_lshlrev_b32_e32 v118, 16, v30
	v_and_b32_e32 v121, 0xffff0000, v31
	v_and_b32_e32 v120, 0xffff0000, v30
	v_pk_add_f32 v[28:29], v[28:29], v[36:37]
	v_lshlrev_b32_e32 v31, 16, v21
	v_lshlrev_b32_e32 v30, 16, v20
	v_lshlrev_b32_e32 v129, 16, v39
	v_lshlrev_b32_e32 v128, 16, v38
	v_and_b32_e32 v131, 0xffff0000, v39
	v_and_b32_e32 v130, 0xffff0000, v38
	v_pk_add_f32 v[38:39], v[28:29], v[30:31]
	v_lshlrev_b32_e32 v29, 16, v45
	v_lshlrev_b32_e32 v28, 16, v44
	v_and_b32_e32 v112, 0xffff0000, v48
	v_and_b32_e32 v113, 0xffff0000, v49
	v_pk_add_f32 v[38:39], v[38:39], v[28:29]
	v_lshlrev_b32_e32 v49, 16, v41
	v_lshlrev_b32_e32 v48, 16, v40
	v_pk_add_f32 v[38:39], v[38:39], v[48:49]
	v_lshlrev_b32_e32 v49, 16, v61
	v_lshlrev_b32_e32 v48, 16, v60
	v_pk_add_f32 v[38:39], v[38:39], v[48:49]
	v_lshlrev_b32_e32 v49, 16, v57
	v_lshlrev_b32_e32 v48, 16, v56
	v_pk_add_f32 v[38:39], v[38:39], v[48:49]
	v_lshlrev_b32_e32 v49, 16, v75
	v_lshlrev_b32_e32 v48, 16, v74
	v_pk_add_f32 v[140:141], v[134:135], 0 op_sel_hi:[1,0]
	v_pk_add_f32 v[38:39], v[38:39], v[48:49]
	v_lshlrev_b32_e32 v49, 16, v71
	v_lshlrev_b32_e32 v48, 16, v70
	v_pk_add_f32 v[146:147], v[38:39], v[48:49]
	v_pk_add_f32 v[38:39], v[140:141], v[124:125]
	v_and_b32_e32 v107, 0xffff0000, v13
	v_pk_add_f32 v[38:39], v[38:39], v[112:113]
	v_and_b32_e32 v106, 0xffff0000, v12
	v_pk_add_f32 v[12:13], v[38:39], v[106:107]
	v_and_b32_e32 v49, 0xffff0000, v25
	v_and_b32_e32 v48, 0xffff0000, v24
	v_pk_add_f32 v[12:13], v[12:13], v[48:49]
	v_and_b32_e32 v25, 0xffff0000, v21
	v_and_b32_e32 v24, 0xffff0000, v20
	v_or_b32_e32 v2, 2, v4
	v_pk_add_f32 v[20:21], v[12:13], v[24:25]
	v_and_b32_e32 v13, 0xffff0000, v45
	v_and_b32_e32 v12, 0xffff0000, v44
	v_ashrrev_i32_e32 v3, 31, v2
	v_or_b32_e32 v6, 3, v4
	v_pk_add_f32 v[20:21], v[20:21], v[12:13]
	v_and_b32_e32 v39, 0xffff0000, v41
	v_and_b32_e32 v38, 0xffff0000, v40
	v_lshlrev_b64 v[104:105], 10, v[2:3]
	v_ashrrev_i32_e32 v7, 31, v6
	v_pk_add_f32 v[20:21], v[20:21], v[38:39]
	v_and_b32_e32 v39, 0xffff0000, v61
	v_and_b32_e32 v38, 0xffff0000, v60
	v_lshl_add_u64 v[2:3], v[0:1], 0, v[104:105]
	v_lshlrev_b64 v[102:103], 10, v[6:7]
	v_pk_add_f32 v[20:21], v[20:21], v[38:39]
	v_and_b32_e32 v39, 0xffff0000, v57
	v_and_b32_e32 v38, 0xffff0000, v56
	v_lshl_add_u64 v[6:7], v[0:1], 0, v[102:103]
	global_load_dwordx4 v[52:55], v[2:3], off
	global_load_dwordx4 v[32:35], v[6:7], off
	v_pk_add_f32 v[20:21], v[20:21], v[38:39]
	v_and_b32_e32 v39, 0xffff0000, v75
	v_and_b32_e32 v38, 0xffff0000, v74
	v_pk_add_f32 v[142:143], v[128:129], 0 op_sel_hi:[1,0]
	v_pk_add_f32 v[20:21], v[20:21], v[38:39]
	v_and_b32_e32 v39, 0xffff0000, v71
	v_and_b32_e32 v38, 0xffff0000, v70
	v_pk_add_f32 v[70:71], v[20:21], v[38:39]
	v_pk_add_f32 v[20:21], v[142:143], v[118:119]
	v_lshlrev_b32_e32 v57, 16, v15
	v_pk_add_f32 v[20:21], v[20:21], v[110:111]
	v_lshlrev_b32_e32 v56, 16, v14
	v_pk_add_f32 v[20:21], v[20:21], v[56:57]
	v_lshlrev_b32_e32 v41, 16, v27
	v_lshlrev_b32_e32 v40, 16, v26
	v_pk_add_f32 v[20:21], v[20:21], v[40:41]
	v_lshlrev_b32_e32 v39, 16, v23
	v_lshlrev_b32_e32 v38, 16, v22
	v_pk_add_f32 v[44:45], v[20:21], v[38:39]
	v_lshlrev_b32_e32 v21, 16, v47
	v_lshlrev_b32_e32 v20, 16, v46
	v_pk_add_f32 v[44:45], v[44:45], v[20:21]
	v_lshlrev_b32_e32 v61, 16, v43
	v_lshlrev_b32_e32 v60, 16, v42
	v_pk_add_f32 v[44:45], v[44:45], v[60:61]
	v_lshlrev_b32_e32 v61, 16, v63
	v_lshlrev_b32_e32 v60, 16, v62
	v_pk_add_f32 v[44:45], v[44:45], v[60:61]
	v_lshlrev_b32_e32 v61, 16, v59
	v_lshlrev_b32_e32 v60, 16, v58
	v_pk_add_f32 v[44:45], v[44:45], v[60:61]
	v_lshlrev_b32_e32 v61, 16, v77
	v_lshlrev_b32_e32 v60, 16, v76
	v_pk_add_f32 v[144:145], v[130:131], 0 op_sel_hi:[1,0]
	v_pk_add_f32 v[44:45], v[44:45], v[60:61]
	v_lshlrev_b32_e32 v61, 16, v73
	v_lshlrev_b32_e32 v60, 16, v72
	v_pk_add_f32 v[74:75], v[44:45], v[60:61]
	v_pk_add_f32 v[44:45], v[144:145], v[120:121]
	v_and_b32_e32 v61, 0xffff0000, v15
	v_pk_add_f32 v[44:45], v[44:45], v[108:109]
	v_and_b32_e32 v60, 0xffff0000, v14
	v_pk_add_f32 v[14:15], v[44:45], v[60:61]
	v_and_b32_e32 v45, 0xffff0000, v27
	v_and_b32_e32 v44, 0xffff0000, v26
	v_pk_add_f32 v[14:15], v[14:15], v[44:45]
	v_and_b32_e32 v27, 0xffff0000, v23
	v_and_b32_e32 v26, 0xffff0000, v22
	v_pk_add_f32 v[22:23], v[14:15], v[26:27]
	v_and_b32_e32 v15, 0xffff0000, v47
	v_and_b32_e32 v14, 0xffff0000, v46
	v_pk_add_f32 v[22:23], v[22:23], v[14:15]
; __device__ __forceinline__ unsigned pk2(float lo, float hi) { return f2bf(lo) | (f2bf(hi) << 16); }
; template <int W> __device__ __forceinline__ void pool_item(const bf16* xa, bf16* ya, int m0, int cgi) {
;     ...
;     for (int o = 0; o < 8; ++o) { float cur[8]; unpk8(rw[o + W - 1], cur);
; #pragma unroll
;         for (int i = 0; i < 8; ++i) s[i] += cur[i];
;         const int t = t0 + o, cnt = (t + 1 < W) ? t + 1 : W; const float ic = 1.f / (float)cnt; v4u ov;
;         ov.x = pk2(s[0] * ic - cur[0], s[1] * ic - cur[1]); ov.y = pk2(s[2] * ic - cur[2], s[3] * ic - cur[3]); ov.z = pk2(s[4] * ic - cur[4], s[5] * ic - cur[5]); ov.w = pk2(s[6] * ic - cur[6], s[7] * ic - cur[7]);
;         *(v4u*)(ya + (size_t)(m0 + o) * 512 + 8 * cgi) = ov;
;         float old[8]; unpk8(rw[o], old);
; #pragma unroll
;         for (int i = 0; i < 8; ++i) s[i] -= old[i]; }
	v_and_b32_e32 v43, 0xffff0000, v43
	v_and_b32_e32 v42, 0xffff0000, v42
	v_pk_add_f32 v[22:23], v[22:23], v[42:43]
	v_and_b32_e32 v43, 0xffff0000, v63
	v_and_b32_e32 v42, 0xffff0000, v62
	v_pk_add_f32 v[22:23], v[22:23], v[42:43]
	v_and_b32_e32 v43, 0xffff0000, v59
	v_and_b32_e32 v42, 0xffff0000, v58
	v_pk_add_f32 v[22:23], v[22:23], v[42:43]
	v_and_b32_e32 v43, 0xffff0000, v77
	v_and_b32_e32 v42, 0xffff0000, v76
	v_pk_add_f32 v[22:23], v[22:23], v[42:43]
	v_and_b32_e32 v43, 0xffff0000, v73
	v_and_b32_e32 v42, 0xffff0000, v72
	v_pk_add_f32 v[42:43], v[22:23], v[42:43]
	v_min_u32_e32 v22, 15, v139
	v_add_u32_e32 v22, 1, v22
	v_lshlrev_b32_e32 v62, 16, v88
	v_and_b32_e32 v72, 0xffff0000, v88
	v_cvt_f32_ubyte0_e32 v88, v22
	v_lshlrev_b32_e32 v63, 16, v89
	v_and_b32_e32 v73, 0xffff0000, v89
	v_div_scale_f32 v89, s[0:1], v88, v88, 1.0
	v_rcp_f32_e32 v140, v89
	v_lshlrev_b32_e32 v64, 1, v64
	v_lshl_add_u64 v[22:23], s[8:9], 0, v[64:65]
	v_lshlrev_b32_e32 v47, 16, v87
	v_fma_f32 v64, -v89, v140, 1.0
	v_fmac_f32_e32 v140, v64, v140
	v_div_scale_f32 v64, vcc, 1.0, v88, 1.0
	v_mul_f32_e32 v141, v64, v140
	v_lshlrev_b32_e32 v46, 16, v86
	v_and_b32_e32 v59, 0xffff0000, v87
	v_and_b32_e32 v58, 0xffff0000, v86
	v_fma_f32 v142, -v89, v141, v64
	v_lshlrev_b32_e32 v76, 16, v78
	v_and_b32_e32 v78, 0xffff0000, v78
	v_lshlrev_b32_e32 v77, 16, v79
	v_and_b32_e32 v79, 0xffff0000, v79
	v_fmac_f32_e32 v141, v142, v140
	v_pk_add_f32 v[46:47], v[146:147], v[46:47]
	v_pk_add_f32 v[58:59], v[70:71], v[58:59]
	v_lshlrev_b32_e32 v86, 16, v80
	v_lshlrev_b32_e32 v87, 16, v81
	v_fma_f32 v64, -v89, v141, v64
	v_pk_add_f32 v[46:47], v[46:47], v[76:77]
	v_pk_add_f32 v[58:59], v[58:59], v[78:79]
	v_and_b32_e32 v77, 0xffff0000, v83
	v_and_b32_e32 v76, 0xffff0000, v82
	v_pk_add_f32 v[62:63], v[74:75], v[62:63]
	v_and_b32_e32 v80, 0xffff0000, v80
	v_and_b32_e32 v81, 0xffff0000, v81
	v_div_fmas_f32 v64, v64, v140, v141
	v_pk_add_f32 v[58:59], v[58:59], v[76:77]
	s_waitcnt vmcnt(3)
	v_and_b32_e32 v77, 0xffff0000, v91
	v_and_b32_e32 v76, 0xffff0000, v90
	v_pk_add_f32 v[42:43], v[42:43], v[72:73]
	v_pk_add_f32 v[62:63], v[62:63], v[86:87]
	v_lshlrev_b32_e32 v73, 16, v85
	v_lshlrev_b32_e32 v72, 16, v84
	v_div_fixup_f32 v64, v64, v88, 1.0
	v_pk_add_f32 v[58:59], v[58:59], v[76:77]
	v_pk_add_f32 v[42:43], v[42:43], v[80:81]
	v_and_b32_e32 v75, 0xffff0000, v85
	v_and_b32_e32 v74, 0xffff0000, v84
	v_pk_add_f32 v[62:63], v[62:63], v[72:73]
	v_lshlrev_b32_e32 v73, 16, v93
	v_lshlrev_b32_e32 v72, 16, v92
	v_or_b32_e32 v2, 4, v4
	v_lshlrev_b32_e32 v71, 16, v83
	v_lshlrev_b32_e32 v70, 16, v82
	v_pk_fma_f32 v[76:77], v[64:65], v[58:59], v[76:77] op_sel_hi:[0,1,1] neg_lo:[0,0,1] neg_hi:[0,0,1]
	v_pk_add_f32 v[42:43], v[42:43], v[74:75]
	v_and_b32_e32 v75, 0xffff0000, v93
	v_and_b32_e32 v74, 0xffff0000, v92
	v_pk_add_f32 v[62:63], v[62:63], v[72:73]
	v_ashrrev_i32_e32 v3, 31, v2
	v_or_b32_e32 v6, 5, v4
	v_pk_add_f32 v[46:47], v[46:47], v[70:71]
	v_lshlrev_b32_e32 v71, 16, v91
	v_lshlrev_b32_e32 v70, 16, v90
	v_pk_add_f32 v[42:43], v[42:43], v[74:75]
	v_pk_fma_f32 v[72:73], v[64:65], v[62:63], v[72:73] op_sel_hi:[0,1,1] neg_lo:[0,0,1] neg_hi:[0,0,1]
	v_bfe_u32 v80, v76, 16, 1
	v_lshlrev_b64 v[100:101], 10, v[2:3]
	v_ashrrev_i32_e32 v7, 31, v6
	v_pk_add_f32 v[46:47], v[46:47], v[70:71]
	v_pk_fma_f32 v[74:75], v[64:65], v[42:43], v[74:75] op_sel_hi:[0,1,1] neg_lo:[0,0,1] neg_hi:[0,0,1]
	v_add3_u32 v76, v76, v80, s53
	v_bfe_u32 v80, v73, 16, 1
	v_lshl_add_u64 v[2:3], v[0:1], 0, v[100:101]
	v_lshlrev_b64 v[98:99], 10, v[6:7]
	v_pk_fma_f32 v[70:71], v[64:65], v[46:47], v[70:71] op_sel_hi:[0,1,1] neg_lo:[0,0,1] neg_hi:[0,0,1]
	v_bfe_u32 v64, v75, 16, 1
	v_add3_u32 v73, v73, v80, s53
	v_lshl_add_u64 v[6:7], v[0:1], 0, v[98:99]
	global_load_dwordx4 v[16:19], v[2:3], off
	global_load_dwordx4 v[8:11], v[6:7], off
	v_bfe_u32 v78, v74, 16, 1
	v_add3_u32 v64, v75, v64, s53
	v_lshrrev_b32_e32 v73, 16, v73
	v_add3_u32 v74, v74, v78, s53
	v_bfe_u32 v78, v71, 16, 1
	v_and_or_b32 v73, v64, s33, v73
	v_min_u32_e32 v64, 14, v139
	v_bfe_u32 v79, v77, 16, 1
	v_add3_u32 v71, v71, v78, s53
	v_add_u32_e32 v64, 2, v64
	v_add3_u32 v77, v77, v79, s53
	v_lshrrev_b32_e32 v71, 16, v71
	v_cvt_f32_ubyte0_e32 v64, v64
	v_and_or_b32 v71, v77, s33, v71
	v_div_scale_f32 v77, s[0:1], v64, v64, 1.0
	v_or_b32_e32 v2, 6, v4
	v_or_b32_e32 v4, 7, v4
	v_bfe_u32 v75, v70, 16, 1
	v_bfe_u32 v79, v72, 16, 1
	v_rcp_f32_e32 v78, v77
	v_ashrrev_i32_e32 v3, 31, v2
	v_ashrrev_i32_e32 v5, 31, v4
	v_add3_u32 v72, v72, v79, s53
	v_add3_u32 v70, v70, v75, s53
	v_lshlrev_b64 v[96:97], 10, v[2:3]
	v_lshlrev_b64 v[94:95], 10, v[4:5]
	v_lshrrev_b32_e32 v70, 16, v70
	v_lshrrev_b32_e32 v72, 16, v72
	v_lshl_add_u64 v[2:3], v[0:1], 0, v[96:97]
	v_lshl_add_u64 v[0:1], v[0:1], 0, v[94:95]
	v_and_or_b32 v72, v74, s33, v72
	v_and_or_b32 v70, v76, s33, v70
	v_lshl_add_u64 v[74:75], v[22:23], 0, v[126:127]
	global_load_dwordx4 v[4:7], v[2:3], off
	s_nop 0
	global_load_dwordx4 v[0:3], v[0:1], off
	v_pk_add_f32 v[58:59], v[58:59], v[134:135] neg_lo:[0,1] neg_hi:[0,1]
	global_store_dwordx4 v[74:75], v[70:73], off sc1
	v_pk_add_f32 v[42:43], v[42:43], v[130:131] neg_lo:[0,1] neg_hi:[0,1]
	v_pk_add_f32 v[46:47], v[46:47], v[132:133] neg_lo:[0,1] neg_hi:[0,1]
	v_fma_f32 v70, -v77, v78, 1.0
	v_fmac_f32_e32 v78, v70, v78
	v_div_scale_f32 v70, vcc, 1.0, v64, 1.0
	v_mul_f32_e32 v71, v70, v78
	v_fma_f32 v72, -v77, v71, v70
	v_fmac_f32_e32 v71, v72, v78
	v_fma_f32 v70, -v77, v71, v70
	v_div_fmas_f32 v70, v70, v78, v71
	v_div_fixup_f32 v64, v70, v64, 1.0
	s_waitcnt vmcnt(7)
; __device__ __forceinline__ unsigned pk2(float lo, float hi) { return f2bf(lo) | (f2bf(hi) << 16); }
; template <int W> __device__ __forceinline__ void pool_item(const bf16* xa, bf16* ya, int m0, int cgi) {
;     ...
;     for (int o = 0; o < 8; ++o) { float cur[8]; unpk8(rw[o + W - 1], cur);
; #pragma unroll
;         for (int i = 0; i < 8; ++i) s[i] += cur[i];
;         const int t = t0 + o, cnt = (t + 1 < W) ? t + 1 : W; const float ic = 1.f / (float)cnt; v4u ov;
;         ov.x = pk2(s[0] * ic - cur[0], s[1] * ic - cur[1]); ov.y = pk2(s[2] * ic - cur[2], s[3] * ic - cur[3]); ov.z = pk2(s[4] * ic - cur[4], s[5] * ic - cur[5]); ov.w = pk2(s[6] * ic - cur[6], s[7] * ic - cur[7]);
;         *(v4u*)(ya + (size_t)(m0 + o) * 512 + 8 * cgi) = ov;
;         float old[8]; unpk8(rw[o], old);
; #pragma unroll
;         for (int i = 0; i < 8; ++i) s[i] -= old[i]; }
	v_lshlrev_b32_e32 v71, 16, v67
	v_lshlrev_b32_e32 v70, 16, v66
	v_and_b32_e32 v67, 0xffff0000, v67
	v_and_b32_e32 v66, 0xffff0000, v66
	v_lshlrev_b32_e32 v73, 16, v69
	v_lshlrev_b32_e32 v72, 16, v68
	v_and_b32_e32 v69, 0xffff0000, v69
	v_and_b32_e32 v68, 0xffff0000, v68
	v_pk_add_f32 v[58:59], v[58:59], v[66:67]
	v_pk_add_f32 v[62:63], v[62:63], v[128:129] neg_lo:[0,1] neg_hi:[0,1]
	v_pk_add_f32 v[42:43], v[42:43], v[68:69]
	v_pk_add_f32 v[46:47], v[46:47], v[70:71]
	v_pk_fma_f32 v[66:67], v[64:65], v[58:59], v[66:67] op_sel_hi:[0,1,1] neg_lo:[0,0,1] neg_hi:[0,0,1]
	v_pk_add_f32 v[62:63], v[62:63], v[72:73]
	v_pk_fma_f32 v[68:69], v[64:65], v[42:43], v[68:69] op_sel_hi:[0,1,1] neg_lo:[0,0,1] neg_hi:[0,0,1]
	v_pk_fma_f32 v[70:71], v[64:65], v[46:47], v[70:71] op_sel_hi:[0,1,1] neg_lo:[0,0,1] neg_hi:[0,0,1]
	v_pk_fma_f32 v[72:73], v[64:65], v[62:63], v[72:73] op_sel_hi:[0,1,1] neg_lo:[0,0,1] neg_hi:[0,0,1]
	v_bfe_u32 v64, v69, 16, 1
	v_bfe_u32 v76, v66, 16, 1
	v_add3_u32 v66, v66, v76, s53
	v_add3_u32 v64, v69, v64, s53
	v_bfe_u32 v69, v70, 16, 1
	v_bfe_u32 v76, v73, 16, 1
	v_add3_u32 v73, v73, v76, s53
	v_add3_u32 v69, v70, v69, s53
	v_bfe_u32 v75, v67, 16, 1
	v_lshrrev_b32_e32 v70, 16, v69
	v_lshrrev_b32_e32 v69, 16, v73
	v_add3_u32 v67, v67, v75, s53
	v_bfe_u32 v75, v72, 16, 1
	v_and_or_b32 v69, v64, s33, v69
	v_min_u32_e32 v64, 13, v139
	v_bfe_u32 v74, v68, 16, 1
	v_add3_u32 v72, v72, v75, s53
	v_add_u32_e32 v64, 3, v64
	v_add3_u32 v68, v68, v74, s53
	v_lshrrev_b32_e32 v72, 16, v72
	v_cvt_f32_ubyte0_e32 v64, v64
	v_and_or_b32 v68, v68, s33, v72
	v_div_scale_f32 v72, s[0:1], v64, v64, 1.0
	v_bfe_u32 v74, v71, 16, 1
	v_rcp_f32_e32 v73, v72
	v_add3_u32 v71, v71, v74, s53
	v_lshrrev_b32_e32 v71, 16, v71
	v_and_or_b32 v67, v67, s33, v71
	v_and_or_b32 v66, v66, s33, v70
	v_lshl_add_u64 v[70:71], v[22:23], 0, v[116:117]
	global_store_dwordx4 v[70:71], v[66:69], off sc1
	v_pk_add_f32 v[42:43], v[42:43], v[120:121] neg_lo:[0,1] neg_hi:[0,1]
	v_pk_add_f32 v[46:47], v[46:47], v[122:123] neg_lo:[0,1] neg_hi:[0,1]
	v_fma_f32 v66, -v72, v73, 1.0
	v_fmac_f32_e32 v73, v66, v73
	v_div_scale_f32 v66, vcc, 1.0, v64, 1.0
	v_mul_f32_e32 v67, v66, v73
	v_fma_f32 v68, -v72, v67, v66
	v_fmac_f32_e32 v67, v68, v73
	v_fma_f32 v66, -v72, v67, v66
	v_div_fmas_f32 v66, v66, v73, v67
	s_waitcnt vmcnt(7)
	v_lshlrev_b32_e32 v69, 16, v55
	v_lshlrev_b32_e32 v68, 16, v54
	v_and_b32_e32 v55, 0xffff0000, v55
	v_and_b32_e32 v54, 0xffff0000, v54
	v_div_fixup_f32 v64, v66, v64, 1.0
	v_lshlrev_b32_e32 v67, 16, v53
	v_lshlrev_b32_e32 v66, 16, v52
	v_pk_add_f32 v[42:43], v[42:43], v[54:55]
	v_pk_add_f32 v[58:59], v[58:59], v[124:125] neg_lo:[0,1] neg_hi:[0,1]
	v_and_b32_e32 v53, 0xffff0000, v53
	v_and_b32_e32 v52, 0xffff0000, v52
	v_pk_add_f32 v[46:47], v[46:47], v[66:67]
	v_pk_add_f32 v[62:63], v[62:63], v[118:119] neg_lo:[0,1] neg_hi:[0,1]
	v_pk_fma_f32 v[54:55], v[64:65], v[42:43], v[54:55] op_sel_hi:[0,1,1] neg_lo:[0,0,1] neg_hi:[0,0,1]
	v_pk_add_f32 v[58:59], v[58:59], v[52:53]
	v_pk_fma_f32 v[66:67], v[64:65], v[46:47], v[66:67] op_sel_hi:[0,1,1] neg_lo:[0,0,1] neg_hi:[0,0,1]
	v_pk_add_f32 v[62:63], v[62:63], v[68:69]
	v_bfe_u32 v70, v54, 16, 1
	v_pk_fma_f32 v[52:53], v[64:65], v[58:59], v[52:53] op_sel_hi:[0,1,1] neg_lo:[0,0,1] neg_hi:[0,0,1]
	v_pk_fma_f32 v[68:69], v[64:65], v[62:63], v[68:69] op_sel_hi:[0,1,1] neg_lo:[0,0,1] neg_hi:[0,0,1]
	v_bfe_u32 v64, v55, 16, 1
	v_add3_u32 v54, v54, v70, s53
	v_bfe_u32 v70, v67, 16, 1
	v_bfe_u32 v71, v53, 16, 1
	v_bfe_u32 v72, v52, 16, 1
	v_add3_u32 v55, v55, v64, s53
	v_bfe_u32 v64, v66, 16, 1
	v_add3_u32 v67, v67, v70, s53
	v_add3_u32 v52, v52, v72, s53
	v_add3_u32 v53, v53, v71, s53
	v_bfe_u32 v71, v68, 16, 1
	v_bfe_u32 v72, v69, 16, 1
	v_add3_u32 v64, v66, v64, s53
	v_lshrrev_b32_e32 v66, 16, v67
	v_add3_u32 v69, v69, v72, s53
	v_add3_u32 v68, v68, v71, s53
	v_and_or_b32 v53, v53, s33, v66
	v_min_u32_e32 v66, 12, v139
	v_lshrrev_b32_e32 v67, 16, v68
	v_lshrrev_b32_e32 v68, 16, v69
	v_add_u32_e32 v66, 4, v66
	v_and_or_b32 v55, v55, s33, v68
	v_cvt_f32_ubyte0_e32 v68, v66
	v_div_scale_f32 v69, s[0:1], v68, v68, 1.0
	v_rcp_f32_e32 v70, v69
	v_lshrrev_b32_e32 v64, 16, v64
	v_and_or_b32 v54, v54, s33, v67
	v_and_or_b32 v52, v52, s33, v64
	v_lshl_add_u64 v[66:67], v[22:23], 0, v[104:105]
	global_store_dwordx4 v[66:67], v[52:55], off sc1
	v_pk_add_f32 v[42:43], v[42:43], v[108:109] neg_lo:[0,1] neg_hi:[0,1]
	s_waitcnt vmcnt(7)
; __device__ __forceinline__ unsigned pk2(float lo, float hi) { return f2bf(lo) | (f2bf(hi) << 16); }
; template <int W> __device__ __forceinline__ void pool_item(const bf16* xa, bf16* ya, int m0, int cgi) {
;     ...
;     for (int o = 0; o < 8; ++o) { float cur[8]; unpk8(rw[o + W - 1], cur);
; #pragma unroll
;         for (int i = 0; i < 8; ++i) s[i] += cur[i];
;         const int t = t0 + o, cnt = (t + 1 < W) ? t + 1 : W; const float ic = 1.f / (float)cnt; v4u ov;
;         ov.x = pk2(s[0] * ic - cur[0], s[1] * ic - cur[1]); ov.y = pk2(s[2] * ic - cur[2], s[3] * ic - cur[3]); ov.z = pk2(s[4] * ic - cur[4], s[5] * ic - cur[5]); ov.w = pk2(s[6] * ic - cur[6], s[7] * ic - cur[7]);
;         *(v4u*)(ya + (size_t)(m0 + o) * 512 + 8 * cgi) = ov;
;         float old[8]; unpk8(rw[o], old);
; #pragma unroll
;         for (int i = 0; i < 8; ++i) s[i] -= old[i]; }
	v_lshlrev_b32_e32 v67, 16, v35
	v_fma_f32 v52, -v69, v70, 1.0
	v_fmac_f32_e32 v70, v52, v70
	v_div_scale_f32 v52, vcc, 1.0, v68, 1.0
	v_mul_f32_e32 v53, v52, v70
	v_fma_f32 v54, -v69, v53, v52
	v_fmac_f32_e32 v53, v54, v70
	v_fma_f32 v52, -v69, v53, v52
	v_div_fmas_f32 v52, v52, v70, v53
	v_lshlrev_b32_e32 v66, 16, v34
	v_and_b32_e32 v35, 0xffff0000, v35
	v_and_b32_e32 v34, 0xffff0000, v34
	v_div_fixup_f32 v52, v52, v68, 1.0
	v_pk_add_f32 v[46:47], v[46:47], v[114:115] neg_lo:[0,1] neg_hi:[0,1]
	v_pk_add_f32 v[54:55], v[58:59], v[112:113] neg_lo:[0,1] neg_hi:[0,1]
	v_lshlrev_b32_e32 v59, 16, v33
	v_lshlrev_b32_e32 v58, 16, v32
	v_and_b32_e32 v33, 0xffff0000, v33
	v_and_b32_e32 v32, 0xffff0000, v32
	v_pk_add_f32 v[62:63], v[62:63], v[110:111] neg_lo:[0,1] neg_hi:[0,1]
	v_pk_add_f32 v[42:43], v[42:43], v[34:35]
	v_pk_add_f32 v[46:47], v[46:47], v[58:59]
	v_pk_add_f32 v[54:55], v[54:55], v[32:33]
	v_pk_add_f32 v[62:63], v[62:63], v[66:67]
	v_pk_fma_f32 v[34:35], v[52:53], v[42:43], v[34:35] op_sel_hi:[0,1,1] neg_lo:[0,0,1] neg_hi:[0,0,1]
	v_pk_fma_f32 v[58:59], v[52:53], v[46:47], v[58:59] op_sel_hi:[0,1,1] neg_lo:[0,0,1] neg_hi:[0,0,1]
	v_pk_fma_f32 v[32:33], v[52:53], v[54:55], v[32:33] op_sel_hi:[0,1,1] neg_lo:[0,0,1] neg_hi:[0,0,1]
	v_pk_fma_f32 v[66:67], v[52:53], v[62:63], v[66:67] op_sel_hi:[0,1,1] neg_lo:[0,0,1] neg_hi:[0,0,1]
	v_bfe_u32 v53, v34, 16, 1
	v_add3_u32 v34, v34, v53, s53
	v_bfe_u32 v53, v59, 16, 1
	v_bfe_u32 v64, v33, 16, 1
	v_add3_u32 v53, v59, v53, s53
	v_bfe_u32 v52, v35, 16, 1
	v_bfe_u32 v68, v32, 16, 1
	v_add3_u32 v33, v33, v64, s53
	v_bfe_u32 v64, v66, 16, 1
	v_lshrrev_b32_e32 v53, 16, v53
	v_add3_u32 v32, v32, v68, s53
	v_add3_u32 v35, v35, v52, s53
	v_bfe_u32 v52, v58, 16, 1
	v_bfe_u32 v68, v67, 16, 1
	v_add3_u32 v64, v66, v64, s53
	v_and_or_b32 v33, v33, s33, v53
	v_min_u32_e32 v53, 11, v139
	v_add3_u32 v67, v67, v68, s53
	v_add3_u32 v52, v58, v52, s53
	v_lshrrev_b32_e32 v58, 16, v64
	v_add_u32_e32 v53, 5, v53
	v_lshrrev_b32_e32 v59, 16, v67
	v_and_or_b32 v34, v34, s33, v58
	v_cvt_f32_ubyte0_e32 v58, v53
	v_and_or_b32 v35, v35, s33, v59
	v_div_scale_f32 v59, s[0:1], v58, v58, 1.0
	v_rcp_f32_e32 v64, v59
	v_lshrrev_b32_e32 v52, 16, v52
	v_and_or_b32 v32, v32, s33, v52
	v_lshl_add_u64 v[52:53], v[22:23], 0, v[102:103]
	global_store_dwordx4 v[52:53], v[32:35], off sc1
	v_pk_add_f32 v[42:43], v[42:43], v[60:61] neg_lo:[0,1] neg_hi:[0,1]
	v_pk_add_f32 v[52:53], v[62:63], v[56:57] neg_lo:[0,1] neg_hi:[0,1]
	v_fma_f32 v32, -v59, v64, 1.0
	v_fmac_f32_e32 v64, v32, v64
	v_div_scale_f32 v32, vcc, 1.0, v58, 1.0
	v_mul_f32_e32 v33, v32, v64
	v_fma_f32 v34, -v59, v33, v32
	v_fmac_f32_e32 v33, v34, v64
	v_fma_f32 v32, -v59, v33, v32
	v_div_fmas_f32 v32, v32, v64, v33
	v_pk_add_f32 v[34:35], v[46:47], v[50:51] neg_lo:[0,1] neg_hi:[0,1]
	v_pk_add_f32 v[46:47], v[54:55], v[106:107] neg_lo:[0,1] neg_hi:[0,1]
	s_waitcnt vmcnt(7)
	v_lshlrev_b32_e32 v55, 16, v19
	v_lshlrev_b32_e32 v54, 16, v18
	v_and_b32_e32 v19, 0xffff0000, v19
	v_and_b32_e32 v18, 0xffff0000, v18
	v_div_fixup_f32 v32, v32, v58, 1.0
	v_lshlrev_b32_e32 v51, 16, v17
	v_lshlrev_b32_e32 v50, 16, v16
	v_and_b32_e32 v17, 0xffff0000, v17
	v_and_b32_e32 v16, 0xffff0000, v16
	v_pk_add_f32 v[42:43], v[42:43], v[18:19]
	v_pk_add_f32 v[34:35], v[34:35], v[50:51]
	v_pk_add_f32 v[46:47], v[46:47], v[16:17]
	v_pk_add_f32 v[52:53], v[52:53], v[54:55]
	v_pk_fma_f32 v[18:19], v[32:33], v[42:43], v[18:19] op_sel_hi:[0,1,1] neg_lo:[0,0,1] neg_hi:[0,0,1]
	v_pk_fma_f32 v[50:51], v[32:33], v[34:35], v[50:51] op_sel_hi:[0,1,1] neg_lo:[0,0,1] neg_hi:[0,0,1]
	v_pk_fma_f32 v[16:17], v[32:33], v[46:47], v[16:17] op_sel_hi:[0,1,1] neg_lo:[0,0,1] neg_hi:[0,0,1]
	v_pk_fma_f32 v[54:55], v[32:33], v[52:53], v[54:55] op_sel_hi:[0,1,1] neg_lo:[0,0,1] neg_hi:[0,0,1]
	v_bfe_u32 v33, v18, 16, 1
	v_add3_u32 v18, v18, v33, s53
	v_bfe_u32 v33, v51, 16, 1
	v_bfe_u32 v56, v17, 16, 1
	v_add3_u32 v33, v51, v33, s53
	v_bfe_u32 v32, v19, 16, 1
	v_bfe_u32 v57, v16, 16, 1
	v_add3_u32 v17, v17, v56, s53
	v_bfe_u32 v56, v54, 16, 1
	v_lshrrev_b32_e32 v33, 16, v33
	v_add3_u32 v16, v16, v57, s53
	v_add3_u32 v19, v19, v32, s53
	v_bfe_u32 v32, v50, 16, 1
	v_bfe_u32 v57, v55, 16, 1
	v_add3_u32 v54, v54, v56, s53
	v_and_or_b32 v17, v17, s33, v33
	v_min_u32_e32 v33, 10, v139
	v_add3_u32 v55, v55, v57, s53
	v_add3_u32 v32, v50, v32, s53
	v_lshrrev_b32_e32 v50, 16, v54
	v_add_u32_e32 v33, 6, v33
	v_lshrrev_b32_e32 v51, 16, v55
	v_and_or_b32 v18, v18, s33, v50
	v_cvt_f32_ubyte0_e32 v50, v33
	v_and_or_b32 v19, v19, s33, v51
	v_div_scale_f32 v51, s[0:1], v50, v50, 1.0
	v_rcp_f32_e32 v54, v51
	v_lshrrev_b32_e32 v32, 16, v32
	v_and_or_b32 v16, v16, s33, v32
	v_lshl_add_u64 v[32:33], v[22:23], 0, v[100:101]
	global_store_dwordx4 v[32:33], v[16:19], off sc1
	v_pk_add_f32 v[32:33], v[46:47], v[48:49] neg_lo:[0,1] neg_hi:[0,1]
	s_nop 0
	v_fma_f32 v16, -v51, v54, 1.0
	v_fmac_f32_e32 v54, v16, v54
	v_div_scale_f32 v16, vcc, 1.0, v50, 1.0
	v_mul_f32_e32 v17, v16, v54
	v_fma_f32 v18, -v51, v17, v16
	v_fmac_f32_e32 v17, v18, v54
	v_fma_f32 v16, -v51, v17, v16
	v_div_fmas_f32 v16, v16, v54, v17
	v_pk_add_f32 v[18:19], v[34:35], v[36:37] neg_lo:[0,1] neg_hi:[0,1]
	v_pk_add_f32 v[36:37], v[52:53], v[40:41] neg_lo:[0,1] neg_hi:[0,1]
	v_pk_add_f32 v[40:41], v[42:43], v[44:45] neg_lo:[0,1] neg_hi:[0,1]
	s_waitcnt vmcnt(7)
; __device__ __forceinline__ unsigned pk2(float lo, float hi) { return f2bf(lo) | (f2bf(hi) << 16); }
; template <int W> __device__ __forceinline__ void pool_item(const bf16* xa, bf16* ya, int m0, int cgi) {
;     ...
;     for (int o = 0; o < 8; ++o) { float cur[8]; unpk8(rw[o + W - 1], cur);
; #pragma unroll
;         for (int i = 0; i < 8; ++i) s[i] += cur[i];
;         const int t = t0 + o, cnt = (t + 1 < W) ? t + 1 : W; const float ic = 1.f / (float)cnt; v4u ov;
;         ov.x = pk2(s[0] * ic - cur[0], s[1] * ic - cur[1]); ov.y = pk2(s[2] * ic - cur[2], s[3] * ic - cur[3]); ov.z = pk2(s[4] * ic - cur[4], s[5] * ic - cur[5]); ov.w = pk2(s[6] * ic - cur[6], s[7] * ic - cur[7]);
;         *(v4u*)(ya + (size_t)(m0 + o) * 512 + 8 * cgi) = ov;
;         float old[8]; unpk8(rw[o], old);
; #pragma unroll
;         for (int i = 0; i < 8; ++i) s[i] -= old[i]; }
	v_lshlrev_b32_e32 v43, 16, v11
	v_lshlrev_b32_e32 v42, 16, v10
	v_and_b32_e32 v11, 0xffff0000, v11
	v_and_b32_e32 v10, 0xffff0000, v10
	v_div_fixup_f32 v16, v16, v50, 1.0
	v_lshlrev_b32_e32 v35, 16, v9
	v_lshlrev_b32_e32 v34, 16, v8
	v_and_b32_e32 v9, 0xffff0000, v9
	v_and_b32_e32 v8, 0xffff0000, v8
	v_pk_add_f32 v[40:41], v[40:41], v[10:11]
	v_pk_add_f32 v[18:19], v[18:19], v[34:35]
	v_pk_add_f32 v[32:33], v[32:33], v[8:9]
	v_pk_add_f32 v[36:37], v[36:37], v[42:43]
	v_pk_fma_f32 v[10:11], v[16:17], v[40:41], v[10:11] op_sel_hi:[0,1,1] neg_lo:[0,0,1] neg_hi:[0,0,1]
	v_pk_fma_f32 v[34:35], v[16:17], v[18:19], v[34:35] op_sel_hi:[0,1,1] neg_lo:[0,0,1] neg_hi:[0,0,1]
	v_pk_fma_f32 v[8:9], v[16:17], v[32:33], v[8:9] op_sel_hi:[0,1,1] neg_lo:[0,0,1] neg_hi:[0,0,1]
	v_pk_fma_f32 v[42:43], v[16:17], v[36:37], v[42:43] op_sel_hi:[0,1,1] neg_lo:[0,0,1] neg_hi:[0,0,1]
	v_bfe_u32 v17, v10, 16, 1
	v_add3_u32 v10, v10, v17, s53
	v_bfe_u32 v17, v35, 16, 1
	v_bfe_u32 v44, v9, 16, 1
	v_add3_u32 v17, v35, v17, s53
	v_bfe_u32 v16, v11, 16, 1
	v_bfe_u32 v45, v8, 16, 1
	v_add3_u32 v9, v9, v44, s53
	v_bfe_u32 v44, v42, 16, 1
	v_lshrrev_b32_e32 v17, 16, v17
	v_add3_u32 v8, v8, v45, s53
	v_add3_u32 v11, v11, v16, s53
	v_bfe_u32 v16, v34, 16, 1
	v_bfe_u32 v45, v43, 16, 1
	v_add3_u32 v42, v42, v44, s53
	v_and_or_b32 v9, v9, s33, v17
	v_min_u32_e32 v17, 9, v139
	v_add3_u32 v43, v43, v45, s53
	v_add3_u32 v16, v34, v16, s53
	v_lshrrev_b32_e32 v34, 16, v42
	v_add_u32_e32 v17, 7, v17
	v_lshrrev_b32_e32 v35, 16, v43
	v_and_or_b32 v10, v10, s33, v34
	v_cvt_f32_ubyte0_e32 v34, v17
	v_and_or_b32 v11, v11, s33, v35
	v_div_scale_f32 v35, s[0:1], v34, v34, 1.0
	v_rcp_f32_e32 v42, v35
	v_lshrrev_b32_e32 v16, 16, v16
	v_and_or_b32 v8, v8, s33, v16
	v_lshl_add_u64 v[16:17], v[22:23], 0, v[98:99]
	global_store_dwordx4 v[16:17], v[8:11], off sc1
	v_pk_add_f32 v[26:27], v[40:41], v[26:27] neg_lo:[0,1] neg_hi:[0,1]
	v_pk_add_f32 v[16:17], v[32:33], v[24:25] neg_lo:[0,1] neg_hi:[0,1]
	v_fma_f32 v8, -v35, v42, 1.0
	v_fmac_f32_e32 v42, v8, v42
	v_div_scale_f32 v8, vcc, 1.0, v34, 1.0
	v_mul_f32_e32 v9, v8, v42
	v_fma_f32 v10, -v35, v9, v8
	v_fmac_f32_e32 v9, v10, v42
	v_fma_f32 v8, -v35, v9, v8
	v_div_fmas_f32 v8, v8, v42, v9
	v_pk_add_f32 v[10:11], v[18:19], v[30:31] neg_lo:[0,1] neg_hi:[0,1]
	s_waitcnt vmcnt(7)
	v_lshlrev_b32_e32 v31, 16, v7
	v_lshlrev_b32_e32 v30, 16, v6
	v_and_b32_e32 v7, 0xffff0000, v7
	v_and_b32_e32 v6, 0xffff0000, v6
	v_div_fixup_f32 v8, v8, v34, 1.0
	v_lshlrev_b32_e32 v19, 16, v5
	v_lshlrev_b32_e32 v18, 16, v4
	v_and_b32_e32 v5, 0xffff0000, v5
	v_and_b32_e32 v4, 0xffff0000, v4
	v_pk_add_f32 v[24:25], v[36:37], v[38:39] neg_lo:[0,1] neg_hi:[0,1]
	v_pk_add_f32 v[26:27], v[26:27], v[6:7]
	v_pk_add_f32 v[10:11], v[10:11], v[18:19]
	v_pk_add_f32 v[16:17], v[16:17], v[4:5]
	v_pk_add_f32 v[24:25], v[24:25], v[30:31]
	v_pk_fma_f32 v[6:7], v[8:9], v[26:27], v[6:7] op_sel_hi:[0,1,1] neg_lo:[0,0,1] neg_hi:[0,0,1]
	v_pk_fma_f32 v[18:19], v[8:9], v[10:11], v[18:19] op_sel_hi:[0,1,1] neg_lo:[0,0,1] neg_hi:[0,0,1]
	v_pk_fma_f32 v[4:5], v[8:9], v[16:17], v[4:5] op_sel_hi:[0,1,1] neg_lo:[0,0,1] neg_hi:[0,0,1]
	v_pk_fma_f32 v[30:31], v[8:9], v[24:25], v[30:31] op_sel_hi:[0,1,1] neg_lo:[0,0,1] neg_hi:[0,0,1]
	v_bfe_u32 v9, v6, 16, 1
	v_add3_u32 v6, v6, v9, s53
	v_bfe_u32 v9, v19, 16, 1
	v_bfe_u32 v32, v5, 16, 1
	v_add3_u32 v9, v19, v9, s53
	v_bfe_u32 v8, v7, 16, 1
	v_bfe_u32 v33, v4, 16, 1
	v_add3_u32 v5, v5, v32, s53
	v_bfe_u32 v32, v30, 16, 1
	v_lshrrev_b32_e32 v9, 16, v9
	v_add3_u32 v4, v4, v33, s53
	v_add3_u32 v7, v7, v8, s53
	v_bfe_u32 v8, v18, 16, 1
	v_bfe_u32 v33, v31, 16, 1
	v_add3_u32 v30, v30, v32, s53
	v_and_or_b32 v5, v5, s33, v9
	v_min_u32_e32 v9, 8, v139
	v_add3_u32 v31, v31, v33, s53
	v_add3_u32 v8, v18, v8, s53
	v_lshrrev_b32_e32 v18, 16, v30
	v_add_u32_e32 v9, 8, v9
	v_lshrrev_b32_e32 v19, 16, v31
	v_and_or_b32 v6, v6, s33, v18
	v_cvt_f32_ubyte0_e32 v18, v9
	v_and_or_b32 v7, v7, s33, v19
	v_div_scale_f32 v19, s[0:1], v18, v18, 1.0
	v_rcp_f32_e32 v30, v19
	v_lshrrev_b32_e32 v8, 16, v8
	v_and_or_b32 v4, v4, s33, v8
	v_lshl_add_u64 v[8:9], v[22:23], 0, v[96:97]
	global_store_dwordx4 v[8:9], v[4:7], off sc1
	v_pk_add_f32 v[8:9], v[16:17], v[12:13] neg_lo:[0,1] neg_hi:[0,1]
	s_waitcnt vmcnt(7)
	v_lshlrev_b32_e32 v13, 16, v3
	v_fma_f32 v4, -v19, v30, 1.0
	v_fmac_f32_e32 v30, v4, v30
	v_div_scale_f32 v4, vcc, 1.0, v18, 1.0
	v_mul_f32_e32 v5, v4, v30
	v_fma_f32 v6, -v19, v5, v4
	v_fmac_f32_e32 v5, v6, v30
	v_fma_f32 v4, -v19, v5, v4
	v_div_fmas_f32 v4, v4, v30, v5
	v_pk_add_f32 v[6:7], v[10:11], v[28:29] neg_lo:[0,1] neg_hi:[0,1]
	v_lshlrev_b32_e32 v11, 16, v1
	v_lshlrev_b32_e32 v10, 16, v0
	v_div_fixup_f32 v4, v4, v18, 1.0
	v_and_b32_e32 v1, 0xffff0000, v1
	v_and_b32_e32 v0, 0xffff0000, v0
	v_pk_add_f32 v[6:7], v[6:7], v[10:11]
	v_pk_add_f32 v[8:9], v[8:9], v[0:1]
	v_pk_fma_f32 v[6:7], v[4:5], v[6:7], v[10:11] op_sel_hi:[0,1,1] neg_lo:[0,0,1] neg_hi:[0,0,1]
	v_pk_add_f32 v[10:11], v[26:27], v[14:15] neg_lo:[0,1] neg_hi:[0,1]
	v_lshlrev_b32_e32 v12, 16, v2
	v_and_b32_e32 v3, 0xffff0000, v3
	v_and_b32_e32 v2, 0xffff0000, v2
	v_pk_fma_f32 v[0:1], v[4:5], v[8:9], v[0:1] op_sel_hi:[0,1,1] neg_lo:[0,0,1] neg_hi:[0,0,1]
	v_pk_add_f32 v[8:9], v[24:25], v[20:21] neg_lo:[0,1] neg_hi:[0,1]
	v_pk_add_f32 v[10:11], v[10:11], v[2:3]
	v_pk_add_f32 v[8:9], v[8:9], v[12:13]
	v_pk_fma_f32 v[2:3], v[4:5], v[10:11], v[2:3] op_sel_hi:[0,1,1] neg_lo:[0,0,1] neg_hi:[0,0,1]
	v_pk_fma_f32 v[8:9], v[4:5], v[8:9], v[12:13] op_sel_hi:[0,1,1] neg_lo:[0,0,1] neg_hi:[0,0,1]
	v_bfe_u32 v4, v3, 16, 1
	v_bfe_u32 v5, v2, 16, 1
	v_bfe_u32 v10, v1, 16, 1
	v_bfe_u32 v11, v0, 16, 1
	v_add3_u32 v0, v0, v11, s53
	v_add3_u32 v1, v1, v10, s53
	v_add3_u32 v2, v2, v5, s53
	v_add3_u32 v3, v3, v4, s53
	v_bfe_u32 v4, v6, 16, 1
	v_bfe_u32 v5, v7, 16, 1
	v_bfe_u32 v10, v8, 16, 1
	v_bfe_u32 v11, v9, 16, 1
	v_add3_u32 v9, v9, v11, s53
	v_add3_u32 v8, v8, v10, s53
	v_add3_u32 v5, v7, v5, s53
	v_add3_u32 v4, v6, v4, s53
	v_lshrrev_b32_e32 v4, 16, v4
	v_lshrrev_b32_e32 v5, 16, v5
	v_lshrrev_b32_e32 v6, 16, v8
	v_lshrrev_b32_e32 v7, 16, v9
	v_and_or_b32 v3, v3, s33, v7
	v_and_or_b32 v2, v2, s33, v6
	v_and_or_b32 v1, v1, s33, v5
	v_and_or_b32 v0, v0, s33, v4
	v_lshl_add_u64 v[4:5], v[22:23], 0, v[94:95]
	global_store_dwordx4 v[4:5], v[0:3], off sc1

; template <int W> __device__ __forceinline__ void pool_item(const bf16* xa, bf16* ya, int m0, int cgi) {
;     const int t0 = m0 & (SEQ - 1); v4u rw[W + 7];
; #pragma unroll
;     for (int a = 0; a < W + 7; ++a) { const int tl = a - (W - 1); rw[a] = (t0 + tl >= 0) ? *(const v4u*)(xa + (size_t)(m0 + tl) * 512 + 8 * cgi) : (v4u){0u, 0u, 0u, 0u}; }
;     float s[8];
; #pragma unroll
;     for (int i = 0; i < 8; ++i) s[i] = 0.f;
; #pragma unroll
;     for (int a = 0; a < W - 1; ++a) { float xf[8]; unpk8(rw[a], xf);
; #pragma unroll
;         for (int i = 0; i < 8; ++i) s[i] += xf[i]; }
; #pragma unroll
;     for (int o = 0; o < 8; ++o) { float cur[8]; unpk8(rw[o + W - 1], cur);
; #pragma unroll
;         for (int i = 0; i < 8; ++i) s[i] += cur[i];
;         const int t = t0 + o, cnt = (t + 1 < W) ? t + 1 : W; const float ic = 1.f / (float)cnt; v4u ov;
.LBB0_757:
	s_or_b64 exec, exec, s[16:17]
	v_ashrrev_i32_e32 v5, 31, v4
	v_or_b32_e32 v6, 1, v4
	v_lshlrev_b64 v[100:101], 10, v[4:5]
	v_ashrrev_i32_e32 v7, 31, v6
	v_lshlrev_b32_e32 v64, 3, v2
	v_lshl_add_u64 v[2:3], v[0:1], 0, v[100:101]
	v_lshlrev_b64 v[90:91], 10, v[6:7]
	v_lshl_add_u64 v[6:7], v[0:1], 0, v[90:91]
	global_load_dwordx4 v[106:109], v[2:3], off
	global_load_dwordx4 v[32:35], v[6:7], off
	v_or_b32_e32 v2, 2, v4
	v_ashrrev_i32_e32 v3, 31, v2
	v_or_b32_e32 v6, 3, v4
	v_lshlrev_b64 v[80:81], 10, v[2:3]
	v_ashrrev_i32_e32 v7, 31, v6
	v_lshl_add_u64 v[2:3], v[0:1], 0, v[80:81]
	v_lshlrev_b64 v[66:67], 10, v[6:7]
	v_lshl_add_u64 v[6:7], v[0:1], 0, v[66:67]
	global_load_dwordx4 v[20:23], v[2:3], off
	global_load_dwordx4 v[16:19], v[6:7], off
	s_waitcnt vmcnt(4)
	v_and_b32_e32 v115, 0xffff0000, v29
	v_and_b32_e32 v114, 0xffff0000, v28
	v_lshlrev_b32_e32 v111, 16, v29
	v_lshlrev_b32_e32 v110, 16, v28
	v_pk_add_f32 v[28:29], v[114:115], 0 op_sel_hi:[1,0]
	v_and_b32_e32 v97, 0xffff0000, v25
	v_and_b32_e32 v96, 0xffff0000, v24
	v_lshlrev_b32_e32 v95, 16, v25
	v_lshlrev_b32_e32 v94, 16, v24
	v_pk_add_f32 v[24:25], v[28:29], v[96:97]
	v_and_b32_e32 v87, 0xffff0000, v41
	v_and_b32_e32 v86, 0xffff0000, v40
	v_pk_add_f32 v[24:25], v[24:25], v[86:87]
	v_and_b32_e32 v77, 0xffff0000, v37
	v_and_b32_e32 v76, 0xffff0000, v36
	v_lshlrev_b32_e32 v117, 16, v31
	v_lshlrev_b32_e32 v116, 16, v30
	v_pk_add_f32 v[28:29], v[24:25], v[76:77]
	v_pk_add_f32 v[24:25], v[116:117], 0 op_sel_hi:[1,0]
	v_lshlrev_b32_e32 v99, 16, v27
	v_lshlrev_b32_e32 v98, 16, v26
	v_pk_add_f32 v[24:25], v[24:25], v[98:99]
	v_lshlrev_b32_e32 v89, 16, v43
	v_lshlrev_b32_e32 v88, 16, v42
	v_pk_add_f32 v[24:25], v[24:25], v[88:89]
	v_lshlrev_b32_e32 v79, 16, v39
	v_lshlrev_b32_e32 v78, 16, v38
	v_and_b32_e32 v119, 0xffff0000, v31
	v_and_b32_e32 v118, 0xffff0000, v30
	v_lshlrev_b32_e32 v85, 16, v41
	v_lshlrev_b32_e32 v84, 16, v40
	v_pk_add_f32 v[40:41], v[24:25], v[78:79]
	v_pk_add_f32 v[24:25], v[118:119], 0 op_sel_hi:[1,0]
	v_and_b32_e32 v103, 0xffff0000, v27
	v_and_b32_e32 v102, 0xffff0000, v26
	v_pk_add_f32 v[24:25], v[24:25], v[102:103]
	v_and_b32_e32 v93, 0xffff0000, v43
	v_and_b32_e32 v92, 0xffff0000, v42
	v_pk_add_f32 v[24:25], v[24:25], v[92:93]
	v_and_b32_e32 v83, 0xffff0000, v39
	v_and_b32_e32 v82, 0xffff0000, v38
	v_pk_add_f32 v[38:39], v[24:25], v[82:83]
	v_min_u32_e32 v24, 7, v104
	v_add_u32_e32 v24, 1, v24
	v_cvt_f32_ubyte0_e32 v26, v24
	v_div_scale_f32 v27, s[0:1], v26, v26, 1.0
	v_lshlrev_b32_e32 v70, 16, v52
	v_and_b32_e32 v72, 0xffff0000, v52
	v_lshlrev_b32_e32 v52, 16, v44
	v_and_b32_e32 v42, 0xffff0000, v44
	v_rcp_f32_e32 v44, v27
	v_lshlrev_b32_e32 v71, 16, v53
	v_and_b32_e32 v73, 0xffff0000, v53
	v_lshlrev_b32_e32 v53, 16, v45
	v_and_b32_e32 v43, 0xffff0000, v45
	v_fma_f32 v45, -v27, v44, 1.0
	v_fmac_f32_e32 v44, v45, v44
	v_div_scale_f32 v45, vcc, 1.0, v26, 1.0
	v_lshlrev_b32_e32 v74, 16, v36
	v_lshlrev_b32_e32 v36, 16, v46
	v_and_b32_e32 v30, 0xffff0000, v46
	v_mul_f32_e32 v46, v45, v44
	v_pk_add_f32 v[68:69], v[110:111], 0 op_sel_hi:[1,0]
	v_lshlrev_b32_e32 v75, 16, v37
	v_lshlrev_b32_e32 v37, 16, v47
	v_and_b32_e32 v31, 0xffff0000, v47
	v_fma_f32 v47, -v27, v46, v45
	v_pk_add_f32 v[68:69], v[68:69], v[94:95]
	v_fmac_f32_e32 v46, v47, v44
	v_pk_add_f32 v[68:69], v[68:69], v[84:85]
	v_fma_f32 v27, -v27, v46, v45
	v_pk_add_f32 v[112:113], v[68:69], v[74:75]
	v_div_fmas_f32 v27, v27, v44, v46
	v_div_fixup_f32 v44, v27, v26, 1.0
	v_pk_add_f32 v[26:27], v[112:113], v[70:71]
	v_pk_add_f32 v[28:29], v[28:29], v[72:73]
	v_pk_add_f32 v[46:47], v[26:27], v[52:53]
	v_pk_add_f32 v[112:113], v[28:29], v[42:43]
	v_lshlrev_b32_e32 v27, 16, v49
	v_lshlrev_b32_e32 v26, 16, v48
	v_and_b32_e32 v29, 0xffff0000, v49
	v_and_b32_e32 v28, 0xffff0000, v48
	v_lshlrev_b32_e32 v69, 16, v55
	v_lshlrev_b32_e32 v68, 16, v54
	v_and_b32_e32 v55, 0xffff0000, v55
	v_and_b32_e32 v54, 0xffff0000, v54
	v_pk_add_f32 v[46:47], v[46:47], v[26:27]
	v_pk_add_f32 v[48:49], v[112:113], v[28:29]
	s_waitcnt vmcnt(3)
	v_lshlrev_b32_e32 v113, 16, v107
	v_lshlrev_b32_e32 v112, 16, v106
	v_pk_add_f32 v[120:121], v[46:47], v[112:113]
	v_pk_add_f32 v[40:41], v[40:41], v[68:69]
	v_pk_add_f32 v[38:39], v[38:39], v[54:55]
	v_pk_fma_f32 v[46:47], v[44:45], v[120:121], v[112:113] op_sel_hi:[0,1,1] neg_lo:[0,0,1] neg_hi:[0,0,1]
	v_pk_add_f32 v[112:113], v[40:41], v[36:37]
	v_pk_add_f32 v[122:123], v[38:39], v[30:31]
	v_lshlrev_b32_e32 v39, 16, v51
	v_lshlrev_b32_e32 v38, 16, v50
	v_and_b32_e32 v41, 0xffff0000, v51
	v_and_b32_e32 v40, 0xffff0000, v50
	v_and_b32_e32 v107, 0xffff0000, v107
	v_and_b32_e32 v106, 0xffff0000, v106
	v_pk_add_f32 v[50:51], v[112:113], v[38:39]
	v_pk_add_f32 v[112:113], v[122:123], v[40:41]
	v_lshlrev_b32_e32 v123, 16, v109
	v_lshlrev_b32_e32 v122, 16, v108
	v_and_b32_e32 v109, 0xffff0000, v109
	v_and_b32_e32 v108, 0xffff0000, v108
	v_pk_add_f32 v[48:49], v[48:49], v[106:107]
	v_pk_add_f32 v[50:51], v[50:51], v[122:123]
	v_pk_add_f32 v[112:113], v[112:113], v[108:109]
	v_lshlrev_b32_e32 v64, 1, v64
	v_pk_fma_f32 v[106:107], v[44:45], v[48:49], v[106:107] op_sel_hi:[0,1,1] neg_lo:[0,0,1] neg_hi:[0,0,1]
	v_pk_fma_f32 v[122:123], v[44:45], v[50:51], v[122:123] op_sel_hi:[0,1,1] neg_lo:[0,0,1] neg_hi:[0,0,1]
	v_pk_fma_f32 v[44:45], v[44:45], v[112:113], v[108:109] op_sel_hi:[0,1,1] neg_lo:[0,0,1] neg_hi:[0,0,1]
	v_lshl_add_u64 v[24:25], s[8:9], 0, v[64:65]
	v_bfe_u32 v64, v45, 16, 1
	v_bfe_u32 v109, v107, 16, 1
	v_or_b32_e32 v2, 4, v4
	v_add3_u32 v107, v107, v109, s53
	v_add3_u32 v45, v45, v64, s53
	v_bfe_u32 v64, v46, 16, 1
	v_bfe_u32 v109, v122, 16, 1
	v_ashrrev_i32_e32 v3, 31, v2
; __device__ __forceinline__ unsigned pk2(float lo, float hi) { return f2bf(lo) | (f2bf(hi) << 16); }
; template <int W> __device__ __forceinline__ void pool_item(const bf16* xa, bf16* ya, int m0, int cgi) {
;     ...
;     for (int o = 0; o < 8; ++o) { float cur[8]; unpk8(rw[o + W - 1], cur);
; #pragma unroll
;         for (int i = 0; i < 8; ++i) s[i] += cur[i];
;         const int t = t0 + o, cnt = (t + 1 < W) ? t + 1 : W; const float ic = 1.f / (float)cnt; v4u ov;
;         ov.x = pk2(s[0] * ic - cur[0], s[1] * ic - cur[1]); ov.y = pk2(s[2] * ic - cur[2], s[3] * ic - cur[3]); ov.z = pk2(s[4] * ic - cur[4], s[5] * ic - cur[5]); ov.w = pk2(s[6] * ic - cur[6], s[7] * ic - cur[7]);
;         *(v4u*)(ya + (size_t)(m0 + o) * 512 + 8 * cgi) = ov;
;         float old[8]; unpk8(rw[o], old);
; #pragma unroll
;         for (int i = 0; i < 8; ++i) s[i] -= old[i]; }
	v_or_b32_e32 v6, 5, v4
	v_bfe_u32 v108, v44, 16, 1
	v_bfe_u32 v124, v106, 16, 1
	v_add3_u32 v109, v122, v109, s53
	v_add3_u32 v46, v46, v64, s53
	v_lshlrev_b64 v[62:63], 10, v[2:3]
	v_ashrrev_i32_e32 v7, 31, v6
	v_add3_u32 v106, v106, v124, s53
	v_add3_u32 v44, v44, v108, s53
	v_bfe_u32 v108, v47, 16, 1
	v_bfe_u32 v124, v123, 16, 1
	v_lshrrev_b32_e32 v64, 16, v46
	v_lshrrev_b32_e32 v46, 16, v109
	v_lshl_add_u64 v[2:3], v[0:1], 0, v[62:63]
	v_lshlrev_b64 v[60:61], 10, v[6:7]
	v_add3_u32 v123, v123, v124, s53
	v_add3_u32 v47, v47, v108, s53
	v_and_or_b32 v46, v44, s33, v46
	v_min_u32_e32 v44, 6, v104
	v_lshl_add_u64 v[6:7], v[0:1], 0, v[60:61]
	global_load_dwordx4 v[12:15], v[2:3], off
	global_load_dwordx4 v[8:11], v[6:7], off
	v_lshrrev_b32_e32 v108, 16, v47
	v_lshrrev_b32_e32 v47, 16, v123
	v_add_u32_e32 v44, 2, v44
	v_and_or_b32 v47, v45, s33, v47
	v_and_or_b32 v45, v107, s33, v108
	v_cvt_f32_ubyte0_e32 v107, v44
	v_div_scale_f32 v108, s[0:1], v107, v107, 1.0
	v_or_b32_e32 v2, 6, v4
	v_or_b32_e32 v4, 7, v4
	v_rcp_f32_e32 v109, v108
	v_ashrrev_i32_e32 v3, 31, v2
	v_ashrrev_i32_e32 v5, 31, v4
	v_lshlrev_b64 v[58:59], 10, v[2:3]
	v_lshlrev_b64 v[56:57], 10, v[4:5]
	v_lshl_add_u64 v[2:3], v[0:1], 0, v[58:59]
	v_lshl_add_u64 v[0:1], v[0:1], 0, v[56:57]
	v_and_or_b32 v44, v106, s33, v64
	v_lshl_add_u64 v[100:101], v[24:25], 0, v[100:101]
	global_load_dwordx4 v[4:7], v[2:3], off
	s_nop 0
	global_load_dwordx4 v[0:3], v[0:1], off
	v_pk_add_f32 v[48:49], v[48:49], v[114:115] neg_lo:[0,1] neg_hi:[0,1]
	global_store_dwordx4 v[100:101], v[44:47], off sc1
	s_waitcnt vmcnt(7)
	v_lshlrev_b32_e32 v101, 16, v33
	v_lshlrev_b32_e32 v100, 16, v32
	v_fma_f32 v44, -v108, v109, 1.0
	v_fmac_f32_e32 v109, v44, v109
	v_div_scale_f32 v44, vcc, 1.0, v107, 1.0
	v_mul_f32_e32 v45, v44, v109
	v_fma_f32 v46, -v108, v45, v44
	v_fmac_f32_e32 v45, v46, v109
	v_fma_f32 v44, -v108, v45, v44
	v_div_fmas_f32 v44, v44, v109, v45
	v_div_fixup_f32 v44, v44, v107, 1.0
	v_pk_add_f32 v[106:107], v[112:113], v[118:119] neg_lo:[0,1] neg_hi:[0,1]
	v_lshlrev_b32_e32 v109, 16, v35
	v_lshlrev_b32_e32 v108, 16, v34
	v_and_b32_e32 v35, 0xffff0000, v35
	v_and_b32_e32 v34, 0xffff0000, v34
	v_pk_add_f32 v[46:47], v[120:121], v[110:111] neg_lo:[0,1] neg_hi:[0,1]
	v_and_b32_e32 v33, 0xffff0000, v33
	v_and_b32_e32 v32, 0xffff0000, v32
	v_pk_add_f32 v[50:51], v[50:51], v[116:117] neg_lo:[0,1] neg_hi:[0,1]
	v_pk_add_f32 v[106:107], v[106:107], v[34:35]
	v_pk_add_f32 v[46:47], v[46:47], v[100:101]
	v_pk_add_f32 v[48:49], v[48:49], v[32:33]
	v_pk_add_f32 v[50:51], v[50:51], v[108:109]
	v_pk_fma_f32 v[34:35], v[44:45], v[106:107], v[34:35] op_sel_hi:[0,1,1] neg_lo:[0,0,1] neg_hi:[0,0,1]
	v_pk_fma_f32 v[100:101], v[44:45], v[46:47], v[100:101] op_sel_hi:[0,1,1] neg_lo:[0,0,1] neg_hi:[0,0,1]
	v_pk_fma_f32 v[32:33], v[44:45], v[48:49], v[32:33] op_sel_hi:[0,1,1] neg_lo:[0,0,1] neg_hi:[0,0,1]
	v_pk_fma_f32 v[108:109], v[44:45], v[50:51], v[108:109] op_sel_hi:[0,1,1] neg_lo:[0,0,1] neg_hi:[0,0,1]
	v_bfe_u32 v45, v34, 16, 1
	v_add3_u32 v34, v34, v45, s53
	v_bfe_u32 v45, v101, 16, 1
	v_bfe_u32 v64, v33, 16, 1
	v_add3_u32 v45, v101, v45, s53
	v_bfe_u32 v110, v32, 16, 1
	v_add3_u32 v33, v33, v64, s53
	v_bfe_u32 v64, v108, 16, 1
	v_lshrrev_b32_e32 v45, 16, v45
	v_bfe_u32 v44, v35, 16, 1
	v_add3_u32 v32, v32, v110, s53
	v_bfe_u32 v110, v109, 16, 1
	v_add3_u32 v64, v108, v64, s53
	v_and_or_b32 v33, v33, s33, v45
	v_min_u32_e32 v45, 5, v104
	v_add3_u32 v35, v35, v44, s53
	v_bfe_u32 v44, v100, 16, 1
	v_add3_u32 v109, v109, v110, s53
	v_lshrrev_b32_e32 v64, 16, v64
	v_add_u32_e32 v45, 3, v45
	v_add3_u32 v44, v100, v44, s53
	v_lshrrev_b32_e32 v100, 16, v109
	v_and_or_b32 v34, v34, s33, v64
	v_cvt_f32_ubyte0_e32 v64, v45
	v_and_or_b32 v35, v35, s33, v100
	v_div_scale_f32 v100, s[0:1], v64, v64, 1.0
	v_rcp_f32_e32 v101, v100
	v_lshrrev_b32_e32 v44, 16, v44
	v_and_or_b32 v32, v32, s33, v44
	v_lshl_add_u64 v[44:45], v[24:25], 0, v[90:91]
	global_store_dwordx4 v[44:45], v[32:35], off sc1
	v_pk_add_f32 v[44:45], v[48:49], v[96:97] neg_lo:[0,1] neg_hi:[0,1]
	v_pk_add_f32 v[48:49], v[50:51], v[98:99] neg_lo:[0,1] neg_hi:[0,1]
	v_fma_f32 v32, -v100, v101, 1.0
	v_fmac_f32_e32 v101, v32, v101
	v_div_scale_f32 v32, vcc, 1.0, v64, 1.0
	v_mul_f32_e32 v33, v32, v101
	v_fma_f32 v34, -v100, v33, v32
	v_fmac_f32_e32 v33, v34, v101
	v_fma_f32 v32, -v100, v33, v32
	v_div_fmas_f32 v32, v32, v101, v33
	v_pk_add_f32 v[50:51], v[106:107], v[102:103] neg_lo:[0,1] neg_hi:[0,1]
	s_waitcnt vmcnt(7)
; __device__ __forceinline__ unsigned pk2(float lo, float hi) { return f2bf(lo) | (f2bf(hi) << 16); }
; template <int W> __device__ __forceinline__ void pool_item(const bf16* xa, bf16* ya, int m0, int cgi) {
;     ...
;     for (int o = 0; o < 8; ++o) { float cur[8]; unpk8(rw[o + W - 1], cur);
; #pragma unroll
;         for (int i = 0; i < 8; ++i) s[i] += cur[i];
;         const int t = t0 + o, cnt = (t + 1 < W) ? t + 1 : W; const float ic = 1.f / (float)cnt; v4u ov;
;         ov.x = pk2(s[0] * ic - cur[0], s[1] * ic - cur[1]); ov.y = pk2(s[2] * ic - cur[2], s[3] * ic - cur[3]); ov.z = pk2(s[4] * ic - cur[4], s[5] * ic - cur[5]); ov.w = pk2(s[6] * ic - cur[6], s[7] * ic - cur[7]);
;         *(v4u*)(ya + (size_t)(m0 + o) * 512 + 8 * cgi) = ov;
;         float old[8]; unpk8(rw[o], old);
; #pragma unroll
;         for (int i = 0; i < 8; ++i) s[i] -= old[i]; }
	v_lshlrev_b32_e32 v91, 16, v23
	v_lshlrev_b32_e32 v90, 16, v22
	v_and_b32_e32 v23, 0xffff0000, v23
	v_and_b32_e32 v22, 0xffff0000, v22
	v_div_fixup_f32 v32, v32, v64, 1.0
	v_pk_add_f32 v[34:35], v[46:47], v[94:95] neg_lo:[0,1] neg_hi:[0,1]
	v_lshlrev_b32_e32 v47, 16, v21
	v_lshlrev_b32_e32 v46, 16, v20
	v_and_b32_e32 v21, 0xffff0000, v21
	v_and_b32_e32 v20, 0xffff0000, v20
	v_pk_add_f32 v[50:51], v[50:51], v[22:23]
	v_pk_add_f32 v[34:35], v[34:35], v[46:47]
	v_pk_add_f32 v[44:45], v[44:45], v[20:21]
	v_pk_add_f32 v[48:49], v[48:49], v[90:91]
	v_pk_fma_f32 v[22:23], v[32:33], v[50:51], v[22:23] op_sel_hi:[0,1,1] neg_lo:[0,0,1] neg_hi:[0,0,1]
	v_pk_fma_f32 v[46:47], v[32:33], v[34:35], v[46:47] op_sel_hi:[0,1,1] neg_lo:[0,0,1] neg_hi:[0,0,1]
	v_pk_fma_f32 v[20:21], v[32:33], v[44:45], v[20:21] op_sel_hi:[0,1,1] neg_lo:[0,0,1] neg_hi:[0,0,1]
	v_pk_fma_f32 v[90:91], v[32:33], v[48:49], v[90:91] op_sel_hi:[0,1,1] neg_lo:[0,0,1] neg_hi:[0,0,1]
	v_bfe_u32 v33, v22, 16, 1
	v_add3_u32 v22, v22, v33, s53
	v_bfe_u32 v33, v47, 16, 1
	v_bfe_u32 v64, v21, 16, 1
	v_add3_u32 v33, v47, v33, s53
	v_bfe_u32 v32, v23, 16, 1
	v_bfe_u32 v94, v20, 16, 1
	v_add3_u32 v21, v21, v64, s53
	v_bfe_u32 v64, v90, 16, 1
	v_lshrrev_b32_e32 v33, 16, v33
	v_add3_u32 v20, v20, v94, s53
	v_add3_u32 v23, v23, v32, s53
	v_bfe_u32 v32, v46, 16, 1
	v_bfe_u32 v94, v91, 16, 1
	v_add3_u32 v64, v90, v64, s53
	v_and_or_b32 v21, v21, s33, v33
	v_min_u32_e32 v33, 4, v104
	v_add3_u32 v91, v91, v94, s53
	v_add3_u32 v32, v46, v32, s53
	v_lshrrev_b32_e32 v46, 16, v64
	v_add_u32_e32 v33, 4, v33
	v_lshrrev_b32_e32 v47, 16, v91
	v_and_or_b32 v22, v22, s33, v46
	v_cvt_f32_ubyte0_e32 v46, v33
	v_and_or_b32 v23, v23, s33, v47
	v_div_scale_f32 v47, s[0:1], v46, v46, 1.0
	v_rcp_f32_e32 v64, v47
	v_lshrrev_b32_e32 v32, 16, v32
	v_and_or_b32 v20, v20, s33, v32
	v_lshl_add_u64 v[32:33], v[24:25], 0, v[80:81]
	global_store_dwordx4 v[32:33], v[20:23], off sc1
	v_pk_add_f32 v[32:33], v[44:45], v[86:87] neg_lo:[0,1] neg_hi:[0,1]
	v_pk_add_f32 v[44:45], v[48:49], v[88:89] neg_lo:[0,1] neg_hi:[0,1]
	v_fma_f32 v20, -v47, v64, 1.0
	v_fmac_f32_e32 v64, v20, v64
	v_div_scale_f32 v20, vcc, 1.0, v46, 1.0
	v_mul_f32_e32 v21, v20, v64
	v_fma_f32 v22, -v47, v21, v20
	v_fmac_f32_e32 v21, v22, v64
	v_fma_f32 v20, -v47, v21, v20
	v_div_fmas_f32 v20, v20, v64, v21
	v_div_fixup_f32 v20, v20, v46, 1.0
	v_pk_add_f32 v[46:47], v[50:51], v[92:93] neg_lo:[0,1] neg_hi:[0,1]
	s_waitcnt vmcnt(7)
	v_lshlrev_b32_e32 v49, 16, v19
	v_lshlrev_b32_e32 v48, 16, v18
	v_and_b32_e32 v19, 0xffff0000, v19
	v_and_b32_e32 v18, 0xffff0000, v18
	v_pk_add_f32 v[22:23], v[34:35], v[84:85] neg_lo:[0,1] neg_hi:[0,1]
	v_lshlrev_b32_e32 v35, 16, v17
	v_lshlrev_b32_e32 v34, 16, v16
	v_and_b32_e32 v17, 0xffff0000, v17
	v_and_b32_e32 v16, 0xffff0000, v16
	v_pk_add_f32 v[46:47], v[46:47], v[18:19]
	v_pk_add_f32 v[22:23], v[22:23], v[34:35]
	v_pk_add_f32 v[32:33], v[32:33], v[16:17]
	v_pk_add_f32 v[44:45], v[44:45], v[48:49]
	v_pk_fma_f32 v[18:19], v[20:21], v[46:47], v[18:19] op_sel_hi:[0,1,1] neg_lo:[0,0,1] neg_hi:[0,0,1]
	v_pk_fma_f32 v[34:35], v[20:21], v[22:23], v[34:35] op_sel_hi:[0,1,1] neg_lo:[0,0,1] neg_hi:[0,0,1]
	v_pk_fma_f32 v[16:17], v[20:21], v[32:33], v[16:17] op_sel_hi:[0,1,1] neg_lo:[0,0,1] neg_hi:[0,0,1]
	v_pk_fma_f32 v[48:49], v[20:21], v[44:45], v[48:49] op_sel_hi:[0,1,1] neg_lo:[0,0,1] neg_hi:[0,0,1]
	v_bfe_u32 v21, v18, 16, 1
	v_add3_u32 v18, v18, v21, s53
	v_bfe_u32 v21, v35, 16, 1
	v_bfe_u32 v50, v17, 16, 1
	v_add3_u32 v21, v35, v21, s53
	v_bfe_u32 v20, v19, 16, 1
	v_bfe_u32 v51, v16, 16, 1
	v_add3_u32 v17, v17, v50, s53
	v_bfe_u32 v50, v48, 16, 1
	v_lshrrev_b32_e32 v21, 16, v21
	v_add3_u32 v16, v16, v51, s53
	v_add3_u32 v19, v19, v20, s53
	v_bfe_u32 v20, v34, 16, 1
	v_bfe_u32 v51, v49, 16, 1
	v_add3_u32 v48, v48, v50, s53
	v_and_or_b32 v17, v17, s33, v21
	v_min_u32_e32 v21, 3, v104
	v_add3_u32 v49, v49, v51, s53
	v_add3_u32 v20, v34, v20, s53
	v_lshrrev_b32_e32 v34, 16, v48
	v_add_u32_e32 v21, 5, v21
	v_lshrrev_b32_e32 v35, 16, v49
	v_and_or_b32 v18, v18, s33, v34
	v_cvt_f32_ubyte0_e32 v34, v21
	v_and_or_b32 v19, v19, s33, v35
	v_div_scale_f32 v35, s[0:1], v34, v34, 1.0
	v_rcp_f32_e32 v48, v35
	v_lshrrev_b32_e32 v20, 16, v20
	v_and_or_b32 v16, v16, s33, v20
	v_lshl_add_u64 v[20:21], v[24:25], 0, v[66:67]
	global_store_dwordx4 v[20:21], v[16:19], off sc1
	v_pk_add_f32 v[20:21], v[32:33], v[76:77] neg_lo:[0,1] neg_hi:[0,1]
	v_pk_add_f32 v[32:33], v[44:45], v[78:79] neg_lo:[0,1] neg_hi:[0,1]
	v_fma_f32 v16, -v35, v48, 1.0
	v_fmac_f32_e32 v48, v16, v48
	v_div_scale_f32 v16, vcc, 1.0, v34, 1.0
	v_mul_f32_e32 v17, v16, v48
	v_fma_f32 v18, -v35, v17, v16
	v_fmac_f32_e32 v17, v18, v48
	v_fma_f32 v16, -v35, v17, v16
	v_div_fmas_f32 v16, v16, v48, v17
	v_div_fixup_f32 v16, v16, v34, 1.0
	v_pk_add_f32 v[34:35], v[46:47], v[82:83] neg_lo:[0,1] neg_hi:[0,1]
	s_waitcnt vmcnt(7)
; __device__ __forceinline__ unsigned pk2(float lo, float hi) { return f2bf(lo) | (f2bf(hi) << 16); }
; template <int W> __device__ __forceinline__ void pool_item(const bf16* xa, bf16* ya, int m0, int cgi) {
;     ...
;     for (int o = 0; o < 8; ++o) { float cur[8]; unpk8(rw[o + W - 1], cur);
; #pragma unroll
;         for (int i = 0; i < 8; ++i) s[i] += cur[i];
;         const int t = t0 + o, cnt = (t + 1 < W) ? t + 1 : W; const float ic = 1.f / (float)cnt; v4u ov;
;         ov.x = pk2(s[0] * ic - cur[0], s[1] * ic - cur[1]); ov.y = pk2(s[2] * ic - cur[2], s[3] * ic - cur[3]); ov.z = pk2(s[4] * ic - cur[4], s[5] * ic - cur[5]); ov.w = pk2(s[6] * ic - cur[6], s[7] * ic - cur[7]);
;         *(v4u*)(ya + (size_t)(m0 + o) * 512 + 8 * cgi) = ov;
;         float old[8]; unpk8(rw[o], old);
; #pragma unroll
;         for (int i = 0; i < 8; ++i) s[i] -= old[i]; }
	v_lshlrev_b32_e32 v45, 16, v15
	v_lshlrev_b32_e32 v44, 16, v14
	v_and_b32_e32 v15, 0xffff0000, v15
	v_and_b32_e32 v14, 0xffff0000, v14
	v_pk_add_f32 v[18:19], v[22:23], v[74:75] neg_lo:[0,1] neg_hi:[0,1]
	v_lshlrev_b32_e32 v23, 16, v13
	v_lshlrev_b32_e32 v22, 16, v12
	v_and_b32_e32 v13, 0xffff0000, v13
	v_and_b32_e32 v12, 0xffff0000, v12
	v_pk_add_f32 v[34:35], v[34:35], v[14:15]
	v_pk_add_f32 v[18:19], v[18:19], v[22:23]
	v_pk_add_f32 v[20:21], v[20:21], v[12:13]
	v_pk_add_f32 v[32:33], v[32:33], v[44:45]
	v_pk_fma_f32 v[14:15], v[16:17], v[34:35], v[14:15] op_sel_hi:[0,1,1] neg_lo:[0,0,1] neg_hi:[0,0,1]
	v_pk_fma_f32 v[22:23], v[16:17], v[18:19], v[22:23] op_sel_hi:[0,1,1] neg_lo:[0,0,1] neg_hi:[0,0,1]
	v_pk_fma_f32 v[12:13], v[16:17], v[20:21], v[12:13] op_sel_hi:[0,1,1] neg_lo:[0,0,1] neg_hi:[0,0,1]
	v_pk_fma_f32 v[44:45], v[16:17], v[32:33], v[44:45] op_sel_hi:[0,1,1] neg_lo:[0,0,1] neg_hi:[0,0,1]
	v_bfe_u32 v17, v14, 16, 1
	v_add3_u32 v14, v14, v17, s53
	v_bfe_u32 v17, v23, 16, 1
	v_bfe_u32 v46, v13, 16, 1
	v_add3_u32 v17, v23, v17, s53
	v_bfe_u32 v16, v15, 16, 1
	v_bfe_u32 v47, v12, 16, 1
	v_add3_u32 v13, v13, v46, s53
	v_bfe_u32 v46, v44, 16, 1
	v_lshrrev_b32_e32 v17, 16, v17
	v_add3_u32 v12, v12, v47, s53
	v_add3_u32 v15, v15, v16, s53
	v_bfe_u32 v16, v22, 16, 1
	v_bfe_u32 v47, v45, 16, 1
	v_add3_u32 v44, v44, v46, s53
	v_and_or_b32 v13, v13, s33, v17
	v_min_u32_e32 v17, 2, v104
	v_add3_u32 v45, v45, v47, s53
	v_add3_u32 v16, v22, v16, s53
	v_lshrrev_b32_e32 v22, 16, v44
	v_add_u32_e32 v17, 6, v17
	v_lshrrev_b32_e32 v23, 16, v45
	v_and_or_b32 v14, v14, s33, v22
	v_cvt_f32_ubyte0_e32 v22, v17
	v_and_or_b32 v15, v15, s33, v23
	v_div_scale_f32 v23, s[0:1], v22, v22, 1.0
	v_rcp_f32_e32 v44, v23
	v_lshrrev_b32_e32 v16, 16, v16
	v_and_or_b32 v12, v12, s33, v16
	v_lshl_add_u64 v[16:17], v[24:25], 0, v[62:63]
	global_store_dwordx4 v[16:17], v[12:15], off sc1
	v_pk_add_f32 v[16:17], v[20:21], v[72:73] neg_lo:[0,1] neg_hi:[0,1]
	v_pk_add_f32 v[20:21], v[32:33], v[68:69] neg_lo:[0,1] neg_hi:[0,1]
	v_fma_f32 v12, -v23, v44, 1.0
	v_fmac_f32_e32 v44, v12, v44
	v_div_scale_f32 v12, vcc, 1.0, v22, 1.0
	v_mul_f32_e32 v13, v12, v44
	v_fma_f32 v14, -v23, v13, v12
	v_fmac_f32_e32 v13, v14, v44
	v_fma_f32 v12, -v23, v13, v12
	v_div_fmas_f32 v12, v12, v44, v13
	v_pk_add_f32 v[14:15], v[18:19], v[70:71] neg_lo:[0,1] neg_hi:[0,1]
	s_waitcnt vmcnt(7)
	v_lshlrev_b32_e32 v19, 16, v9
	v_lshlrev_b32_e32 v18, 16, v8
	v_and_b32_e32 v9, 0xffff0000, v9
	v_and_b32_e32 v8, 0xffff0000, v8
	v_div_fixup_f32 v12, v12, v22, 1.0
	v_pk_add_f32 v[16:17], v[16:17], v[8:9]
	v_pk_add_f32 v[22:23], v[34:35], v[54:55] neg_lo:[0,1] neg_hi:[0,1]
	v_lshlrev_b32_e32 v33, 16, v11
	v_lshlrev_b32_e32 v32, 16, v10
	v_and_b32_e32 v11, 0xffff0000, v11
	v_and_b32_e32 v10, 0xffff0000, v10
	v_pk_fma_f32 v[8:9], v[12:13], v[16:17], v[8:9] op_sel_hi:[0,1,1] neg_lo:[0,0,1] neg_hi:[0,0,1]
	v_pk_add_f32 v[20:21], v[20:21], v[32:33]
	v_pk_add_f32 v[22:23], v[22:23], v[10:11]
	v_pk_add_f32 v[14:15], v[14:15], v[18:19]
	v_pk_fma_f32 v[32:33], v[12:13], v[20:21], v[32:33] op_sel_hi:[0,1,1] neg_lo:[0,0,1] neg_hi:[0,0,1]
	v_pk_fma_f32 v[10:11], v[12:13], v[22:23], v[10:11] op_sel_hi:[0,1,1] neg_lo:[0,0,1] neg_hi:[0,0,1]
	v_bfe_u32 v34, v9, 16, 1
	v_pk_fma_f32 v[18:19], v[12:13], v[14:15], v[18:19] op_sel_hi:[0,1,1] neg_lo:[0,0,1] neg_hi:[0,0,1]
	v_bfe_u32 v12, v11, 16, 1
	v_bfe_u32 v35, v8, 16, 1
	v_add3_u32 v9, v9, v34, s53
	v_bfe_u32 v34, v32, 16, 1
	v_bfe_u32 v13, v10, 16, 1
	v_add3_u32 v8, v8, v35, s53
	v_add3_u32 v11, v11, v12, s53
	v_bfe_u32 v12, v18, 16, 1
	v_bfe_u32 v35, v33, 16, 1
	v_add3_u32 v32, v32, v34, s53
	v_add3_u32 v10, v10, v13, s53
	v_bfe_u32 v13, v19, 16, 1
	v_add3_u32 v33, v33, v35, s53
	v_add3_u32 v12, v18, v12, s53
	v_lshrrev_b32_e32 v18, 16, v32
	v_add3_u32 v13, v19, v13, s53
	v_lshrrev_b32_e32 v19, 16, v33
	v_and_or_b32 v10, v10, s33, v18
	v_div_scale_f32 v18, s[0:1], v105, v105, 1.0
	v_and_or_b32 v11, v11, s33, v19
	v_rcp_f32_e32 v19, v18
	v_lshrrev_b32_e32 v12, 16, v12
	v_lshrrev_b32_e32 v13, 16, v13
	v_and_or_b32 v9, v9, s33, v13
	v_and_or_b32 v8, v8, s33, v12
	v_lshl_add_u64 v[12:13], v[24:25], 0, v[60:61]
	global_store_dwordx4 v[12:13], v[8:11], off sc1
	v_pk_add_f32 v[12:13], v[16:17], v[42:43] neg_lo:[0,1] neg_hi:[0,1]
	v_pk_add_f32 v[16:17], v[20:21], v[36:37] neg_lo:[0,1] neg_hi:[0,1]
	v_fma_f32 v8, -v18, v19, 1.0
	v_fmac_f32_e32 v19, v8, v19
	v_div_scale_f32 v8, vcc, 1.0, v105, 1.0
	v_mul_f32_e32 v9, v8, v19
	v_fma_f32 v10, -v18, v9, v8
	v_fmac_f32_e32 v9, v10, v19
	v_fma_f32 v8, -v18, v9, v8
	v_div_fmas_f32 v8, v8, v19, v9
	v_pk_add_f32 v[10:11], v[14:15], v[52:53] neg_lo:[0,1] neg_hi:[0,1]
	s_waitcnt vmcnt(7)
; __device__ __forceinline__ unsigned pk2(float lo, float hi) { return f2bf(lo) | (f2bf(hi) << 16); }
; template <int W> __device__ __forceinline__ void pool_item(const bf16* xa, bf16* ya, int m0, int cgi) {
;     ...
;     for (int o = 0; o < 8; ++o) { float cur[8]; unpk8(rw[o + W - 1], cur);
; #pragma unroll
;         for (int i = 0; i < 8; ++i) s[i] += cur[i];
;         const int t = t0 + o, cnt = (t + 1 < W) ? t + 1 : W; const float ic = 1.f / (float)cnt; v4u ov;
;         ov.x = pk2(s[0] * ic - cur[0], s[1] * ic - cur[1]); ov.y = pk2(s[2] * ic - cur[2], s[3] * ic - cur[3]); ov.z = pk2(s[4] * ic - cur[4], s[5] * ic - cur[5]); ov.w = pk2(s[6] * ic - cur[6], s[7] * ic - cur[7]);
;         *(v4u*)(ya + (size_t)(m0 + o) * 512 + 8 * cgi) = ov;
;         float old[8]; unpk8(rw[o], old);
; #pragma unroll
;         for (int i = 0; i < 8; ++i) s[i] -= old[i]; }
	v_lshlrev_b32_e32 v15, 16, v5
	v_lshlrev_b32_e32 v14, 16, v4
	v_and_b32_e32 v5, 0xffff0000, v5
	v_and_b32_e32 v4, 0xffff0000, v4
	v_pk_add_f32 v[18:19], v[22:23], v[30:31] neg_lo:[0,1] neg_hi:[0,1]
	v_lshlrev_b32_e32 v21, 16, v7
	v_lshlrev_b32_e32 v20, 16, v6
	v_and_b32_e32 v7, 0xffff0000, v7
	v_and_b32_e32 v6, 0xffff0000, v6
	v_div_fixup_f32 v8, v8, v105, 1.0
	v_pk_add_f32 v[12:13], v[12:13], v[4:5]
	v_pk_add_f32 v[18:19], v[18:19], v[6:7]
	v_pk_add_f32 v[10:11], v[10:11], v[14:15]
	v_pk_fma_f32 v[4:5], v[8:9], v[12:13], v[4:5] op_sel_hi:[0,1,1] neg_lo:[0,0,1] neg_hi:[0,0,1]
	v_pk_add_f32 v[16:17], v[16:17], v[20:21]
	v_pk_fma_f32 v[6:7], v[8:9], v[18:19], v[6:7] op_sel_hi:[0,1,1] neg_lo:[0,0,1] neg_hi:[0,0,1]
	v_pk_fma_f32 v[14:15], v[8:9], v[10:11], v[14:15] op_sel_hi:[0,1,1] neg_lo:[0,0,1] neg_hi:[0,0,1]
	v_pk_fma_f32 v[20:21], v[8:9], v[16:17], v[20:21] op_sel_hi:[0,1,1] neg_lo:[0,0,1] neg_hi:[0,0,1]
	v_bfe_u32 v8, v7, 16, 1
	v_bfe_u32 v9, v6, 16, 1
	v_bfe_u32 v22, v5, 16, 1
	v_bfe_u32 v23, v4, 16, 1
	v_add3_u32 v4, v4, v23, s53
	v_add3_u32 v5, v5, v22, s53
	v_add3_u32 v6, v6, v9, s53
	v_add3_u32 v7, v7, v8, s53
	v_bfe_u32 v8, v14, 16, 1
	v_bfe_u32 v9, v15, 16, 1
	v_bfe_u32 v22, v20, 16, 1
	v_bfe_u32 v23, v21, 16, 1
	v_add3_u32 v21, v21, v23, s53
	v_add3_u32 v20, v20, v22, s53
	v_add3_u32 v9, v15, v9, s53
	v_add3_u32 v8, v14, v8, s53
	v_lshrrev_b32_e32 v8, 16, v8
	v_lshrrev_b32_e32 v9, 16, v9
	v_lshrrev_b32_e32 v14, 16, v20
	v_lshrrev_b32_e32 v15, 16, v21
	v_and_or_b32 v7, v7, s33, v15
	v_and_or_b32 v6, v6, s33, v14
	v_and_or_b32 v5, v5, s33, v9
	v_and_or_b32 v4, v4, s33, v8
	v_lshl_add_u64 v[8:9], v[24:25], 0, v[58:59]
	global_store_dwordx4 v[8:9], v[4:7], off sc1
	s_waitcnt vmcnt(7)
	v_lshlrev_b32_e32 v9, 16, v1
	v_lshlrev_b32_e32 v8, 16, v0
	v_pk_add_f32 v[4:5], v[10:11], v[26:27] neg_lo:[0,1] neg_hi:[0,1]
	v_pk_add_f32 v[6:7], v[12:13], v[28:29] neg_lo:[0,1] neg_hi:[0,1]
	v_and_b32_e32 v1, 0xffff0000, v1
	v_and_b32_e32 v0, 0xffff0000, v0
	v_pk_add_f32 v[4:5], v[4:5], v[8:9]
	s_mov_b32 s0, 0x3e000000
	v_pk_add_f32 v[6:7], v[6:7], v[0:1]
	v_pk_fma_f32 v[4:5], v[4:5], s[0:1], v[8:9] op_sel_hi:[1,0,1] neg_lo:[0,0,1] neg_hi:[0,0,1]
	v_pk_add_f32 v[8:9], v[18:19], v[40:41] neg_lo:[0,1] neg_hi:[0,1]
	v_lshlrev_b32_e32 v11, 16, v3
	v_lshlrev_b32_e32 v10, 16, v2
	v_and_b32_e32 v3, 0xffff0000, v3
	v_and_b32_e32 v2, 0xffff0000, v2
	v_pk_fma_f32 v[0:1], v[6:7], s[0:1], v[0:1] op_sel_hi:[1,0,1] neg_lo:[0,0,1] neg_hi:[0,0,1]
	v_pk_add_f32 v[6:7], v[16:17], v[38:39] neg_lo:[0,1] neg_hi:[0,1]
	v_pk_add_f32 v[8:9], v[8:9], v[2:3]
	v_pk_add_f32 v[6:7], v[6:7], v[10:11]
	v_pk_fma_f32 v[2:3], v[8:9], s[0:1], v[2:3] op_sel_hi:[1,0,1] neg_lo:[0,0,1] neg_hi:[0,0,1]
	v_pk_fma_f32 v[6:7], v[6:7], s[0:1], v[10:11] op_sel_hi:[1,0,1] neg_lo:[0,0,1] neg_hi:[0,0,1]
	v_bfe_u32 v8, v3, 16, 1
	v_bfe_u32 v9, v2, 16, 1
	v_bfe_u32 v10, v1, 16, 1
	v_bfe_u32 v11, v0, 16, 1
	v_add3_u32 v0, v0, v11, s53
	v_add3_u32 v1, v1, v10, s53
	v_add3_u32 v2, v2, v9, s53
	v_add3_u32 v3, v3, v8, s53
	v_bfe_u32 v8, v4, 16, 1
	v_bfe_u32 v9, v5, 16, 1
	v_bfe_u32 v10, v6, 16, 1
	v_bfe_u32 v11, v7, 16, 1
	v_add3_u32 v7, v7, v11, s53
	v_add3_u32 v6, v6, v10, s53
	v_add3_u32 v5, v5, v9, s53
	v_add3_u32 v4, v4, v8, s53
	v_lshrrev_b32_e32 v4, 16, v4
	v_lshrrev_b32_e32 v5, 16, v5
	v_lshrrev_b32_e32 v6, 16, v6
	v_lshrrev_b32_e32 v7, 16, v7
	v_and_or_b32 v3, v3, s33, v7
	v_and_or_b32 v2, v2, s33, v6
	v_and_or_b32 v1, v1, s33, v5
	v_and_or_b32 v0, v0, s33, v4
	v_lshl_add_u64 v[4:5], v[24:25], 0, v[56:57]
	global_store_dwordx4 v[4:5], v[0:3], off sc1

; __device__ __forceinline__ unsigned pk2(float lo, float hi) { return f2bf(lo) | (f2bf(hi) << 16); }
; template <int W> __device__ __forceinline__ void pool_item(const bf16* xa, bf16* ya, int m0, int cgi) {
;     const int t0 = m0 & (SEQ - 1); v4u rw[W + 7];
; #pragma unroll
;     for (int a = 0; a < W + 7; ++a) { const int tl = a - (W - 1); rw[a] = (t0 + tl >= 0) ? *(const v4u*)(xa + (size_t)(m0 + tl) * 512 + 8 * cgi) : (v4u){0u, 0u, 0u, 0u}; }
;     float s[8];
; #pragma unroll
;     for (int i = 0; i < 8; ++i) s[i] = 0.f;
; #pragma unroll
;     for (int a = 0; a < W - 1; ++a) { float xf[8]; unpk8(rw[a], xf);
; #pragma unroll
;         for (int i = 0; i < 8; ++i) s[i] += xf[i]; }
; #pragma unroll
;     for (int o = 0; o < 8; ++o) { float cur[8]; unpk8(rw[o + W - 1], cur);
; #pragma unroll
;         for (int i = 0; i < 8; ++i) s[i] += cur[i];
;         const int t = t0 + o, cnt = (t + 1 < W) ? t + 1 : W; const float ic = 1.f / (float)cnt; v4u ov;
;         ov.x = pk2(s[0] * ic - cur[0], s[1] * ic - cur[1]); ov.y = pk2(s[2] * ic - cur[2], s[3] * ic - cur[3]); ov.z = pk2(s[4] * ic - cur[4], s[5] * ic - cur[5]); ov.w = pk2(s[6] * ic - cur[6], s[7] * ic - cur[7]);
;         *(v4u*)(ya + (size_t)(m0 + o) * 512 + 8 * cgi) = ov;
;         float old[8]; unpk8(rw[o], old);
; #pragma unroll
;         for (int i = 0; i < 8; ++i) s[i] -= old[i]; }
.LBB0_763:
	s_or_b64 exec, exec, s[14:15]
	v_ashrrev_i32_e32 v5, 31, v4
	v_lshlrev_b64 v[44:45], 10, v[4:5]
	v_lshl_add_u64 v[8:9], v[6:7], 0, v[44:45]
	global_load_dwordx4 v[28:31], v[8:9], off
	v_or_b32_e32 v8, 1, v4
	v_ashrrev_i32_e32 v9, 31, v8
	v_lshlrev_b64 v[54:55], 10, v[8:9]
	s_waitcnt vmcnt(1)
	v_lshlrev_b32_e32 v47, 16, v1
	v_lshlrev_b32_e32 v46, 16, v0
	v_and_b32_e32 v49, 0xffff0000, v1
	v_and_b32_e32 v48, 0xffff0000, v0
	v_lshl_add_u64 v[0:1], v[6:7], 0, v[54:55]
	global_load_dwordx4 v[32:35], v[0:1], off
	v_or_b32_e32 v10, 2, v4
	v_or_b32_e32 v12, 3, v4
	v_or_b32_e32 v14, 4, v4
	v_or_b32_e32 v18, 5, v4
	v_or_b32_e32 v20, 6, v4
	v_or_b32_e32 v4, 7, v4
	v_ashrrev_i32_e32 v11, 31, v10
	v_ashrrev_i32_e32 v13, 31, v12
	v_ashrrev_i32_e32 v15, 31, v14
	v_ashrrev_i32_e32 v19, 31, v18
	v_ashrrev_i32_e32 v21, 31, v20
	v_ashrrev_i32_e32 v5, 31, v4
	v_lshlrev_b64 v[66:67], 10, v[10:11]
	v_lshlrev_b64 v[68:69], 10, v[12:13]
	v_lshlrev_b64 v[24:25], 10, v[14:15]
	v_lshlrev_b64 v[22:23], 10, v[18:19]
	v_lshlrev_b32_e32 v64, 1, v51
	v_lshlrev_b32_e32 v51, 16, v3
	v_lshlrev_b32_e32 v50, 16, v2
	v_and_b32_e32 v53, 0xffff0000, v3
	v_and_b32_e32 v52, 0xffff0000, v2
	v_lshlrev_b64 v[20:21], 10, v[20:21]
	v_lshlrev_b64 v[18:19], 10, v[4:5]
	v_lshl_add_u64 v[0:1], v[6:7], 0, v[66:67]
	v_lshl_add_u64 v[2:3], v[6:7], 0, v[68:69]
	v_lshl_add_u64 v[4:5], v[6:7], 0, v[24:25]
	v_lshl_add_u64 v[8:9], v[6:7], 0, v[22:23]
	v_lshl_add_u64 v[70:71], v[6:7], 0, v[20:21]
	v_lshl_add_u64 v[72:73], v[6:7], 0, v[18:19]
	global_load_dwordx4 v[36:39], v[0:1], off
	global_load_dwordx4 v[40:43], v[2:3], off
	global_load_dwordx4 v[12:15], v[4:5], off
	s_nop 0
	global_load_dwordx4 v[8:11], v[8:9], off
	s_nop 0
	global_load_dwordx4 v[4:7], v[70:71], off
	global_load_dwordx4 v[0:3], v[72:73], off
	v_div_scale_f32 v27, s[14:15], v26, v26, 1.0
	v_lshl_add_u64 v[16:17], s[8:9], 0, v[64:65]
	v_rcp_f32_e32 v64, v27
	v_div_scale_f32 v74, vcc, 1.0, v26, 1.0
	v_pk_add_f32 v[56:57], v[46:47], 0 op_sel_hi:[1,0]
	v_fma_f32 v70, -v27, v64, 1.0
	v_fmac_f32_e32 v64, v70, v64
	v_mul_f32_e32 v70, v74, v64
	v_fma_f32 v71, -v27, v70, v74
	v_fmac_f32_e32 v70, v71, v64
	v_fma_f32 v27, -v27, v70, v74
	v_pk_add_f32 v[58:59], v[48:49], 0 op_sel_hi:[1,0]
	v_pk_add_f32 v[60:61], v[50:51], 0 op_sel_hi:[1,0]
	v_pk_add_f32 v[62:63], v[52:53], 0 op_sel_hi:[1,0]
	v_div_fmas_f32 v27, v27, v64, v70
	v_div_fixup_f32 v26, v27, v26, 1.0
	v_lshl_add_u64 v[44:45], v[16:17], 0, v[44:45]
	v_lshl_add_u64 v[54:55], v[16:17], 0, v[54:55]
	v_lshl_add_u64 v[24:25], v[16:17], 0, v[24:25]
	v_lshl_add_u64 v[22:23], v[16:17], 0, v[22:23]
	s_waitcnt vmcnt(7)
	v_lshlrev_b32_e32 v71, 16, v29
	v_lshlrev_b32_e32 v70, 16, v28
	v_and_b32_e32 v73, 0xffff0000, v29
	v_and_b32_e32 v72, 0xffff0000, v28
	v_lshlrev_b32_e32 v75, 16, v31
	v_lshlrev_b32_e32 v74, 16, v30
	v_and_b32_e32 v31, 0xffff0000, v31
	v_and_b32_e32 v30, 0xffff0000, v30
	v_pk_add_f32 v[56:57], v[56:57], v[70:71]
	v_pk_add_f32 v[58:59], v[58:59], v[72:73]
	v_pk_add_f32 v[60:61], v[60:61], v[74:75]
	v_pk_add_f32 v[62:63], v[62:63], v[30:31]
	v_pk_fma_f32 v[28:29], v[26:27], v[56:57], v[70:71] op_sel_hi:[0,1,1] neg_lo:[0,0,1] neg_hi:[0,0,1]
	v_pk_fma_f32 v[76:77], v[26:27], v[58:59], v[72:73] op_sel_hi:[0,1,1] neg_lo:[0,0,1] neg_hi:[0,0,1]
	v_pk_fma_f32 v[78:79], v[26:27], v[60:61], v[74:75] op_sel_hi:[0,1,1] neg_lo:[0,0,1] neg_hi:[0,0,1]
	v_pk_fma_f32 v[26:27], v[26:27], v[62:63], v[30:31] op_sel_hi:[0,1,1] neg_lo:[0,0,1] neg_hi:[0,0,1]
	v_bfe_u32 v64, v27, 16, 1
	v_bfe_u32 v80, v26, 16, 1
	v_bfe_u32 v81, v77, 16, 1
	v_bfe_u32 v82, v76, 16, 1
	v_add3_u32 v76, v76, v82, s53
	v_add3_u32 v77, v77, v81, s53
	v_add3_u32 v26, v26, v80, s53
	v_add3_u32 v27, v27, v64, s53
	v_bfe_u32 v64, v28, 16, 1
	v_bfe_u32 v80, v29, 16, 1
	v_bfe_u32 v81, v78, 16, 1
	v_bfe_u32 v82, v79, 16, 1
	v_add3_u32 v79, v79, v82, s53
	v_add3_u32 v78, v78, v81, s53
	v_add3_u32 v29, v29, v80, s53
	v_add3_u32 v28, v28, v64, s53
	v_lshrrev_b32_e32 v64, 16, v28
	v_lshrrev_b32_e32 v80, 16, v29
	v_lshrrev_b32_e32 v28, 16, v78
	v_lshrrev_b32_e32 v29, 16, v79
	v_and_or_b32 v29, v27, s33, v29
	v_and_or_b32 v28, v26, s33, v28
	v_and_or_b32 v27, v77, s33, v80
	v_and_or_b32 v26, v76, s33, v64
	global_store_dwordx4 v[44:45], v[26:29], off sc1
	s_waitcnt vmcnt(7)
	v_lshlrev_b32_e32 v45, 16, v33
	v_lshlrev_b32_e32 v44, 16, v32
	v_pk_add_f32 v[26:27], v[56:57], v[46:47] neg_lo:[0,1] neg_hi:[0,1]
	v_pk_add_f32 v[28:29], v[58:59], v[48:49] neg_lo:[0,1] neg_hi:[0,1]
	v_and_b32_e32 v33, 0xffff0000, v33
	v_and_b32_e32 v32, 0xffff0000, v32
	v_pk_add_f32 v[52:53], v[62:63], v[52:53] neg_lo:[0,1] neg_hi:[0,1]
	v_lshlrev_b32_e32 v57, 16, v35
	v_lshlrev_b32_e32 v56, 16, v34
	v_and_b32_e32 v35, 0xffff0000, v35
	v_and_b32_e32 v34, 0xffff0000, v34
	v_pk_add_f32 v[48:49], v[28:29], v[32:33]
	v_pk_add_f32 v[50:51], v[60:61], v[50:51] neg_lo:[0,1] neg_hi:[0,1]
	v_pk_add_f32 v[52:53], v[52:53], v[34:35]
	v_pk_add_f32 v[46:47], v[26:27], v[44:45]
	v_pk_fma_f32 v[28:29], v[48:49], 0.5, v[32:33] op_sel_hi:[1,0,1] neg_lo:[0,0,1] neg_hi:[0,0,1]
	v_pk_add_f32 v[50:51], v[50:51], v[56:57]
	v_pk_fma_f32 v[60:61], v[52:53], 0.5, v[34:35] op_sel_hi:[1,0,1] neg_lo:[0,0,1] neg_hi:[0,0,1]
	v_pk_fma_f32 v[26:27], v[46:47], 0.5, v[44:45] op_sel_hi:[1,0,1] neg_lo:[0,0,1] neg_hi:[0,0,1]
	v_pk_fma_f32 v[58:59], v[50:51], 0.5, v[56:57] op_sel_hi:[1,0,1] neg_lo:[0,0,1] neg_hi:[0,0,1]
	v_bfe_u32 v62, v61, 16, 1
	v_bfe_u32 v63, v60, 16, 1
	v_bfe_u32 v64, v29, 16, 1
	v_bfe_u32 v76, v28, 16, 1
	v_add3_u32 v76, v28, v76, s53
	v_add3_u32 v64, v29, v64, s53
	v_add3_u32 v28, v60, v63, s53
	v_add3_u32 v29, v61, v62, s53
	v_bfe_u32 v60, v26, 16, 1
	v_bfe_u32 v61, v27, 16, 1
	v_bfe_u32 v62, v58, 16, 1
	v_bfe_u32 v63, v59, 16, 1
	v_add3_u32 v59, v59, v63, s53
	v_add3_u32 v58, v58, v62, s53
	v_add3_u32 v27, v27, v61, s53
	v_add3_u32 v26, v26, v60, s53
	v_lshrrev_b32_e32 v26, 16, v26
	v_lshrrev_b32_e32 v27, 16, v27
	v_lshrrev_b32_e32 v58, 16, v58
	v_lshrrev_b32_e32 v59, 16, v59
	v_and_or_b32 v29, v29, s33, v59
	v_and_or_b32 v28, v28, s33, v58
	v_and_or_b32 v27, v64, s33, v27
	v_and_or_b32 v26, v76, s33, v26
	global_store_dwordx4 v[54:55], v[26:29], off sc1
	v_pk_add_f32 v[30:31], v[52:53], v[30:31] neg_lo:[0,1] neg_hi:[0,1]
	s_waitcnt vmcnt(7)
; __device__ __forceinline__ unsigned pk2(float lo, float hi) { return f2bf(lo) | (f2bf(hi) << 16); }
; template <int W> __device__ __forceinline__ void pool_item(const bf16* xa, bf16* ya, int m0, int cgi) {
;     ...
;     for (int o = 0; o < 8; ++o) { float cur[8]; unpk8(rw[o + W - 1], cur);
; #pragma unroll
;         for (int i = 0; i < 8; ++i) s[i] += cur[i];
;         const int t = t0 + o, cnt = (t + 1 < W) ? t + 1 : W; const float ic = 1.f / (float)cnt; v4u ov;
;         ov.x = pk2(s[0] * ic - cur[0], s[1] * ic - cur[1]); ov.y = pk2(s[2] * ic - cur[2], s[3] * ic - cur[3]); ov.z = pk2(s[4] * ic - cur[4], s[5] * ic - cur[5]); ov.w = pk2(s[6] * ic - cur[6], s[7] * ic - cur[7]);
;         *(v4u*)(ya + (size_t)(m0 + o) * 512 + 8 * cgi) = ov;
;         float old[8]; unpk8(rw[o], old);
; #pragma unroll
;         for (int i = 0; i < 8; ++i) s[i] -= old[i]; }
	v_lshlrev_b32_e32 v53, 16, v39
	v_pk_add_f32 v[26:27], v[46:47], v[70:71] neg_lo:[0,1] neg_hi:[0,1]
	v_pk_add_f32 v[28:29], v[48:49], v[72:73] neg_lo:[0,1] neg_hi:[0,1]
	v_lshlrev_b32_e32 v47, 16, v37
	v_lshlrev_b32_e32 v46, 16, v36
	v_and_b32_e32 v37, 0xffff0000, v37
	v_and_b32_e32 v36, 0xffff0000, v36
	v_lshlrev_b32_e32 v52, 16, v38
	v_and_b32_e32 v39, 0xffff0000, v39
	v_and_b32_e32 v38, 0xffff0000, v38
	v_pk_add_f32 v[54:55], v[28:29], v[36:37]
	v_pk_add_f32 v[50:51], v[50:51], v[74:75] neg_lo:[0,1] neg_hi:[0,1]
	v_pk_add_f32 v[30:31], v[30:31], v[38:39]
	v_pk_add_f32 v[48:49], v[26:27], v[46:47]
	v_pk_fma_f32 v[28:29], v[54:55], 0.5, v[36:37] op_sel_hi:[1,0,1] neg_lo:[0,0,1] neg_hi:[0,0,1]
	v_pk_add_f32 v[50:51], v[50:51], v[52:53]
	v_pk_fma_f32 v[60:61], v[30:31], 0.5, v[38:39] op_sel_hi:[1,0,1] neg_lo:[0,0,1] neg_hi:[0,0,1]
	v_pk_fma_f32 v[26:27], v[48:49], 0.5, v[46:47] op_sel_hi:[1,0,1] neg_lo:[0,0,1] neg_hi:[0,0,1]
	v_pk_fma_f32 v[58:59], v[50:51], 0.5, v[52:53] op_sel_hi:[1,0,1] neg_lo:[0,0,1] neg_hi:[0,0,1]
	v_bfe_u32 v62, v61, 16, 1
	v_bfe_u32 v63, v60, 16, 1
	v_bfe_u32 v64, v29, 16, 1
	v_bfe_u32 v70, v28, 16, 1
	v_add3_u32 v70, v28, v70, s53
	v_add3_u32 v64, v29, v64, s53
	v_add3_u32 v28, v60, v63, s53
	v_add3_u32 v29, v61, v62, s53
	v_bfe_u32 v60, v26, 16, 1
	v_bfe_u32 v61, v27, 16, 1
	v_bfe_u32 v62, v58, 16, 1
	v_bfe_u32 v63, v59, 16, 1
	v_add3_u32 v59, v59, v63, s53
	v_add3_u32 v58, v58, v62, s53
	v_add3_u32 v27, v27, v61, s53
	v_add3_u32 v26, v26, v60, s53
	v_lshrrev_b32_e32 v26, 16, v26
	v_lshrrev_b32_e32 v27, 16, v27
	v_lshrrev_b32_e32 v58, 16, v58
	v_lshrrev_b32_e32 v59, 16, v59
	v_and_or_b32 v29, v29, s33, v59
	v_and_or_b32 v28, v28, s33, v58
	v_and_or_b32 v27, v64, s33, v27
	v_and_or_b32 v26, v70, s33, v26
	v_lshl_add_u64 v[58:59], v[16:17], 0, v[66:67]
	global_store_dwordx4 v[58:59], v[26:29], off sc1
	v_pk_add_f32 v[30:31], v[30:31], v[34:35] neg_lo:[0,1] neg_hi:[0,1]
	s_waitcnt vmcnt(7)
	v_lshlrev_b32_e32 v35, 16, v43
	v_pk_add_f32 v[28:29], v[54:55], v[32:33] neg_lo:[0,1] neg_hi:[0,1]
	v_lshlrev_b32_e32 v33, 16, v41
	v_lshlrev_b32_e32 v32, 16, v40
	v_and_b32_e32 v41, 0xffff0000, v41
	v_and_b32_e32 v40, 0xffff0000, v40
	v_lshlrev_b32_e32 v34, 16, v42
	v_and_b32_e32 v43, 0xffff0000, v43
	v_and_b32_e32 v42, 0xffff0000, v42
	v_pk_add_f32 v[26:27], v[48:49], v[44:45] neg_lo:[0,1] neg_hi:[0,1]
	v_pk_add_f32 v[48:49], v[28:29], v[40:41]
	v_pk_add_f32 v[50:51], v[50:51], v[56:57] neg_lo:[0,1] neg_hi:[0,1]
	v_pk_add_f32 v[30:31], v[30:31], v[42:43]
	v_pk_add_f32 v[44:45], v[26:27], v[32:33]
	v_pk_fma_f32 v[28:29], v[48:49], 0.5, v[40:41] op_sel_hi:[1,0,1] neg_lo:[0,0,1] neg_hi:[0,0,1]
	v_pk_add_f32 v[50:51], v[50:51], v[34:35]
	v_pk_fma_f32 v[56:57], v[30:31], 0.5, v[42:43] op_sel_hi:[1,0,1] neg_lo:[0,0,1] neg_hi:[0,0,1]
	v_pk_fma_f32 v[26:27], v[44:45], 0.5, v[32:33] op_sel_hi:[1,0,1] neg_lo:[0,0,1] neg_hi:[0,0,1]
	v_pk_fma_f32 v[54:55], v[50:51], 0.5, v[34:35] op_sel_hi:[1,0,1] neg_lo:[0,0,1] neg_hi:[0,0,1]
	v_bfe_u32 v58, v57, 16, 1
	v_bfe_u32 v59, v56, 16, 1
	v_bfe_u32 v60, v29, 16, 1
	v_bfe_u32 v61, v28, 16, 1
	v_add3_u32 v61, v28, v61, s53
	v_add3_u32 v60, v29, v60, s53
	v_add3_u32 v28, v56, v59, s53
	v_add3_u32 v29, v57, v58, s53
	v_bfe_u32 v56, v26, 16, 1
	v_bfe_u32 v57, v27, 16, 1
	v_bfe_u32 v58, v54, 16, 1
	v_bfe_u32 v59, v55, 16, 1
	v_add3_u32 v55, v55, v59, s53
	v_add3_u32 v54, v54, v58, s53
	v_add3_u32 v27, v27, v57, s53
	v_add3_u32 v26, v26, v56, s53
	v_lshrrev_b32_e32 v26, 16, v26
	v_lshrrev_b32_e32 v27, 16, v27
	v_lshrrev_b32_e32 v54, 16, v54
	v_lshrrev_b32_e32 v55, 16, v55
	v_and_or_b32 v29, v29, s33, v55
	v_and_or_b32 v28, v28, s33, v54
	v_and_or_b32 v27, v60, s33, v27
	v_and_or_b32 v26, v61, s33, v26
	v_lshl_add_u64 v[54:55], v[16:17], 0, v[68:69]
	global_store_dwordx4 v[54:55], v[26:29], off sc1
	v_pk_add_f32 v[30:31], v[30:31], v[38:39] neg_lo:[0,1] neg_hi:[0,1]
	s_waitcnt vmcnt(7)
	v_lshlrev_b32_e32 v39, 16, v15
	v_pk_add_f32 v[26:27], v[44:45], v[46:47] neg_lo:[0,1] neg_hi:[0,1]
	v_pk_add_f32 v[28:29], v[48:49], v[36:37] neg_lo:[0,1] neg_hi:[0,1]
	v_and_b32_e32 v45, 0xffff0000, v13
	v_and_b32_e32 v44, 0xffff0000, v12
	v_pk_add_f32 v[48:49], v[50:51], v[52:53] neg_lo:[0,1] neg_hi:[0,1]
	v_and_b32_e32 v51, 0xffff0000, v15
	v_and_b32_e32 v50, 0xffff0000, v14
	v_lshlrev_b32_e32 v37, 16, v13
	v_lshlrev_b32_e32 v36, 16, v12
	v_pk_add_f32 v[28:29], v[28:29], v[44:45]
	v_lshlrev_b32_e32 v38, 16, v14
	v_pk_add_f32 v[30:31], v[30:31], v[50:51]
	v_pk_add_f32 v[26:27], v[26:27], v[36:37]
	v_pk_fma_f32 v[46:47], v[28:29], 0.5, v[44:45] op_sel_hi:[1,0,1] neg_lo:[0,0,1] neg_hi:[0,0,1]
	v_pk_add_f32 v[48:49], v[48:49], v[38:39]
	v_pk_fma_f32 v[52:53], v[30:31], 0.5, v[50:51] op_sel_hi:[1,0,1] neg_lo:[0,0,1] neg_hi:[0,0,1]
	v_pk_fma_f32 v[12:13], v[26:27], 0.5, v[36:37] op_sel_hi:[1,0,1] neg_lo:[0,0,1] neg_hi:[0,0,1]
	v_pk_fma_f32 v[14:15], v[48:49], 0.5, v[38:39] op_sel_hi:[1,0,1] neg_lo:[0,0,1] neg_hi:[0,0,1]
	v_bfe_u32 v54, v53, 16, 1
	v_bfe_u32 v55, v52, 16, 1
	v_bfe_u32 v56, v47, 16, 1
	v_bfe_u32 v57, v46, 16, 1
	v_add3_u32 v46, v46, v57, s53
	v_add3_u32 v47, v47, v56, s53
	v_add3_u32 v52, v52, v55, s53
	v_add3_u32 v53, v53, v54, s53
	v_bfe_u32 v54, v12, 16, 1
	v_bfe_u32 v55, v13, 16, 1
	v_bfe_u32 v56, v14, 16, 1
	v_bfe_u32 v57, v15, 16, 1
	v_add3_u32 v15, v15, v57, s53
	v_add3_u32 v14, v14, v56, s53
	v_add3_u32 v13, v13, v55, s53
	v_add3_u32 v12, v12, v54, s53
	v_lshrrev_b32_e32 v12, 16, v12
	v_lshrrev_b32_e32 v13, 16, v13
	v_lshrrev_b32_e32 v14, 16, v14
	v_lshrrev_b32_e32 v15, 16, v15
	v_and_or_b32 v15, v53, s33, v15
	v_and_or_b32 v14, v52, s33, v14
	v_and_or_b32 v13, v47, s33, v13
	v_and_or_b32 v12, v46, s33, v12
	global_store_dwordx4 v[24:25], v[12:15], off sc1
	v_pk_add_f32 v[30:31], v[30:31], v[42:43] neg_lo:[0,1] neg_hi:[0,1]
	s_waitcnt vmcnt(7)
; __device__ __forceinline__ unsigned pk2(float lo, float hi) { return f2bf(lo) | (f2bf(hi) << 16); }
; template <int W> __device__ __forceinline__ void pool_item(const bf16* xa, bf16* ya, int m0, int cgi) {
;     ...
;     for (int o = 0; o < 8; ++o) { float cur[8]; unpk8(rw[o + W - 1], cur);
; #pragma unroll
;         for (int i = 0; i < 8; ++i) s[i] += cur[i];
;         const int t = t0 + o, cnt = (t + 1 < W) ? t + 1 : W; const float ic = 1.f / (float)cnt; v4u ov;
;         ov.x = pk2(s[0] * ic - cur[0], s[1] * ic - cur[1]); ov.y = pk2(s[2] * ic - cur[2], s[3] * ic - cur[3]); ov.z = pk2(s[4] * ic - cur[4], s[5] * ic - cur[5]); ov.w = pk2(s[6] * ic - cur[6], s[7] * ic - cur[7]);
;         *(v4u*)(ya + (size_t)(m0 + o) * 512 + 8 * cgi) = ov;
;         float old[8]; unpk8(rw[o], old);
; #pragma unroll
;         for (int i = 0; i < 8; ++i) s[i] -= old[i]; }
	v_lshlrev_b32_e32 v25, 16, v9
	v_pk_add_f32 v[12:13], v[26:27], v[32:33] neg_lo:[0,1] neg_hi:[0,1]
	v_pk_add_f32 v[14:15], v[28:29], v[40:41] neg_lo:[0,1] neg_hi:[0,1]
	v_and_b32_e32 v27, 0xffff0000, v9
	v_and_b32_e32 v26, 0xffff0000, v8
	v_and_b32_e32 v41, 0xffff0000, v11
	v_and_b32_e32 v40, 0xffff0000, v10
	v_lshlrev_b32_e32 v24, 16, v8
	v_pk_add_f32 v[14:15], v[14:15], v[26:27]
	v_pk_add_f32 v[32:33], v[48:49], v[34:35] neg_lo:[0,1] neg_hi:[0,1]
	v_lshlrev_b32_e32 v35, 16, v11
	v_lshlrev_b32_e32 v34, 16, v10
	v_pk_add_f32 v[30:31], v[30:31], v[40:41]
	v_pk_add_f32 v[12:13], v[12:13], v[24:25]
	v_pk_fma_f32 v[28:29], v[14:15], 0.5, v[26:27] op_sel_hi:[1,0,1] neg_lo:[0,0,1] neg_hi:[0,0,1]
	v_pk_add_f32 v[32:33], v[32:33], v[34:35]
	v_pk_fma_f32 v[42:43], v[30:31], 0.5, v[40:41] op_sel_hi:[1,0,1] neg_lo:[0,0,1] neg_hi:[0,0,1]
	v_pk_fma_f32 v[8:9], v[12:13], 0.5, v[24:25] op_sel_hi:[1,0,1] neg_lo:[0,0,1] neg_hi:[0,0,1]
	v_pk_fma_f32 v[10:11], v[32:33], 0.5, v[34:35] op_sel_hi:[1,0,1] neg_lo:[0,0,1] neg_hi:[0,0,1]
	v_bfe_u32 v46, v43, 16, 1
	v_bfe_u32 v47, v42, 16, 1
	v_bfe_u32 v48, v29, 16, 1
	v_bfe_u32 v49, v28, 16, 1
	v_add3_u32 v28, v28, v49, s53
	v_add3_u32 v29, v29, v48, s53
	v_add3_u32 v42, v42, v47, s53
	v_add3_u32 v43, v43, v46, s53
	v_bfe_u32 v46, v8, 16, 1
	v_bfe_u32 v47, v9, 16, 1
	v_bfe_u32 v48, v10, 16, 1
	v_bfe_u32 v49, v11, 16, 1
	v_add3_u32 v11, v11, v49, s53
	v_add3_u32 v10, v10, v48, s53
	v_add3_u32 v9, v9, v47, s53
	v_add3_u32 v8, v8, v46, s53
	v_lshrrev_b32_e32 v8, 16, v8
	v_lshrrev_b32_e32 v9, 16, v9
	v_lshrrev_b32_e32 v10, 16, v10
	v_lshrrev_b32_e32 v11, 16, v11
	v_and_or_b32 v11, v43, s33, v11
	v_and_or_b32 v10, v42, s33, v10
	v_and_or_b32 v9, v29, s33, v9
	v_and_or_b32 v8, v28, s33, v8
	global_store_dwordx4 v[22:23], v[8:11], off sc1
	v_pk_add_f32 v[22:23], v[30:31], v[50:51] neg_lo:[0,1] neg_hi:[0,1]
	s_waitcnt vmcnt(7)
	v_lshlrev_b32_e32 v29, 16, v7
	v_pk_add_f32 v[8:9], v[12:13], v[36:37] neg_lo:[0,1] neg_hi:[0,1]
	v_pk_add_f32 v[10:11], v[14:15], v[44:45] neg_lo:[0,1] neg_hi:[0,1]
	v_lshlrev_b32_e32 v13, 16, v5
	v_lshlrev_b32_e32 v12, 16, v4
	v_and_b32_e32 v5, 0xffff0000, v5
	v_and_b32_e32 v4, 0xffff0000, v4
	v_lshlrev_b32_e32 v28, 16, v6
	v_and_b32_e32 v7, 0xffff0000, v7
	v_and_b32_e32 v6, 0xffff0000, v6
	v_pk_add_f32 v[10:11], v[10:11], v[4:5]
	v_pk_add_f32 v[14:15], v[32:33], v[38:39] neg_lo:[0,1] neg_hi:[0,1]
	v_pk_add_f32 v[22:23], v[22:23], v[6:7]
	v_pk_add_f32 v[8:9], v[8:9], v[12:13]
	v_pk_fma_f32 v[4:5], v[10:11], 0.5, v[4:5] op_sel_hi:[1,0,1] neg_lo:[0,0,1] neg_hi:[0,0,1]
	v_pk_add_f32 v[14:15], v[14:15], v[28:29]
	v_pk_fma_f32 v[6:7], v[22:23], 0.5, v[6:7] op_sel_hi:[1,0,1] neg_lo:[0,0,1] neg_hi:[0,0,1]
	v_pk_fma_f32 v[12:13], v[8:9], 0.5, v[12:13] op_sel_hi:[1,0,1] neg_lo:[0,0,1] neg_hi:[0,0,1]
	v_pk_fma_f32 v[28:29], v[14:15], 0.5, v[28:29] op_sel_hi:[1,0,1] neg_lo:[0,0,1] neg_hi:[0,0,1]
	v_bfe_u32 v30, v7, 16, 1
	v_bfe_u32 v31, v6, 16, 1
	v_bfe_u32 v32, v5, 16, 1
	v_bfe_u32 v33, v4, 16, 1
	v_add3_u32 v4, v4, v33, s53
	v_add3_u32 v5, v5, v32, s53
	v_add3_u32 v6, v6, v31, s53
	v_add3_u32 v7, v7, v30, s53
	v_bfe_u32 v30, v12, 16, 1
	v_bfe_u32 v31, v13, 16, 1
	v_bfe_u32 v32, v28, 16, 1
	v_bfe_u32 v33, v29, 16, 1
	v_add3_u32 v29, v29, v33, s53
	v_add3_u32 v28, v28, v32, s53
	v_add3_u32 v13, v13, v31, s53
	v_add3_u32 v12, v12, v30, s53
	v_lshrrev_b32_e32 v12, 16, v12
	v_lshrrev_b32_e32 v13, 16, v13
	v_lshrrev_b32_e32 v28, 16, v28
	v_lshrrev_b32_e32 v29, 16, v29
	v_and_or_b32 v7, v7, s33, v29
	v_and_or_b32 v6, v6, s33, v28
	v_and_or_b32 v5, v5, s33, v13
	v_and_or_b32 v4, v4, s33, v12
	v_lshl_add_u64 v[12:13], v[16:17], 0, v[20:21]
	global_store_dwordx4 v[12:13], v[4:7], off sc1
	s_nop 1
	v_pk_add_f32 v[4:5], v[8:9], v[24:25] neg_lo:[0,1] neg_hi:[0,1]
	s_waitcnt vmcnt(7)
	v_lshlrev_b32_e32 v9, 16, v1
	v_lshlrev_b32_e32 v8, 16, v0
	v_pk_add_f32 v[6:7], v[10:11], v[26:27] neg_lo:[0,1] neg_hi:[0,1]
	v_and_b32_e32 v1, 0xffff0000, v1
	v_and_b32_e32 v0, 0xffff0000, v0
	v_pk_add_f32 v[4:5], v[4:5], v[8:9]
	v_pk_add_f32 v[6:7], v[6:7], v[0:1]
	v_pk_fma_f32 v[4:5], v[4:5], 0.5, v[8:9] op_sel_hi:[1,0,1] neg_lo:[0,0,1] neg_hi:[0,0,1]
	v_pk_add_f32 v[8:9], v[22:23], v[40:41] neg_lo:[0,1] neg_hi:[0,1]
	v_lshlrev_b32_e32 v11, 16, v3
	v_lshlrev_b32_e32 v10, 16, v2
	v_and_b32_e32 v3, 0xffff0000, v3
	v_and_b32_e32 v2, 0xffff0000, v2
	v_pk_fma_f32 v[0:1], v[6:7], 0.5, v[0:1] op_sel_hi:[1,0,1] neg_lo:[0,0,1] neg_hi:[0,0,1]
	v_pk_add_f32 v[6:7], v[14:15], v[34:35] neg_lo:[0,1] neg_hi:[0,1]
	v_pk_add_f32 v[8:9], v[8:9], v[2:3]
	v_pk_add_f32 v[6:7], v[6:7], v[10:11]
	v_pk_fma_f32 v[2:3], v[8:9], 0.5, v[2:3] op_sel_hi:[1,0,1] neg_lo:[0,0,1] neg_hi:[0,0,1]
	v_pk_fma_f32 v[6:7], v[6:7], 0.5, v[10:11] op_sel_hi:[1,0,1] neg_lo:[0,0,1] neg_hi:[0,0,1]
	v_bfe_u32 v8, v3, 16, 1
	v_bfe_u32 v9, v2, 16, 1
	v_bfe_u32 v10, v1, 16, 1
	v_bfe_u32 v11, v0, 16, 1
	v_add3_u32 v0, v0, v11, s53
	v_add3_u32 v1, v1, v10, s53
	v_add3_u32 v2, v2, v9, s53
	v_add3_u32 v3, v3, v8, s53
	v_bfe_u32 v8, v4, 16, 1
	v_bfe_u32 v9, v5, 16, 1
	v_bfe_u32 v10, v6, 16, 1
	v_bfe_u32 v11, v7, 16, 1
	v_add3_u32 v7, v7, v11, s53
	v_add3_u32 v6, v6, v10, s53
	v_add3_u32 v5, v5, v9, s53
	v_add3_u32 v4, v4, v8, s53
	v_lshrrev_b32_e32 v4, 16, v4
	v_lshrrev_b32_e32 v5, 16, v5
	v_lshrrev_b32_e32 v6, 16, v6
	v_lshrrev_b32_e32 v7, 16, v7
	v_and_or_b32 v3, v3, s33, v7
	v_and_or_b32 v2, v2, s33, v6
	v_and_or_b32 v1, v1, s33, v5
	v_and_or_b32 v0, v0, s33, v4
	v_lshl_add_u64 v[4:5], v[16:17], 0, v[18:19]
	global_store_dwordx4 v[4:5], v[0:3], off sc1

; __device__ __forceinline__ u32x4 pack8(const f32x4 v0, const f32x4 v1) { u32x4 w; w.x = cvt_pk_bf16(v0[0], v0[1]); w.y = cvt_pk_bf16(v0[2], v0[3]); w.z = cvt_pk_bf16(v1[0], v1[1]); w.w = cvt_pk_bf16(v1[2], v1[3]); return w; }
;     __device__ __forceinline__ void operator()(const f32x4 (&acc)[2][2][4][2], const Unit& u, int wr, int wc, int fr, int fq) const {
;     ...
;         for (int ai = 0; ai < 2; ++ai)
; #pragma unroll
;             for (int m = 0; m < 4; ++m) { const int row = row0 + ai * HALF + m * 16; const float rs = rsv[ai][m];
; #pragma unroll
;                 for (int bj = 0; bj < 2; ++bj) *(u32x4*)(O + (size_t)row * ldc + col0 + bj * HALF) = pack8(acc[ai][bj][m][0] * rs, acc[ai][bj][m][1] * rs); }
; __global__ void __launch_bounds__(NTHR, 2) hybrid_fwd(Args args) {
;     ...
;               { pg8::Gemm g{pb, (const bf16*)(ws + WS_VT) + (size_t)(b * 4 + h) * 65536, 256, 256, KX, 256, 256, 0}; pg8::EpiRs E{qo, D, nullptr, 1.0f};
;                 pg8::gemm_phase<pg8::EpiRs, pg8::OneUnit, true, true>(lds, g, O1, E); }
;               asm volatile("s_waitcnt vmcnt(0)" ::: "memory"); if (uid + G < 256) __builtin_amdgcn_fence(__ATOMIC_ACQUIRE, "agent"); __syncthreads();
;           } }
.LBB0_1300:
	s_lshl_b64 s[0:1], s[14:15], 1
	s_add_u32 s0, s62, s0
	s_addc_u32 s1, s63, s1
	s_lshl_b32 s14, s30, 1
	s_add_u32 s0, s0, s14
	v_ashrrev_i32_e32 v131, 31, v130
	s_addc_u32 s1, s1, 0
	v_or_b32_e32 v64, s23, v142
	v_cvt_pk_bf16_f32 v122, v122, v123
	v_cvt_pk_bf16_f32 v123, v124, v125
	v_cvt_pk_bf16_f32 v124, v126, v127
	v_lshlrev_b64 v[126:127], 11, v[130:131]
	v_or_b32_e32 v132, 16, v130
	v_lshl_add_u64 v[126:127], s[0:1], 0, v[126:127]
	v_lshlrev_b32_e32 v64, 1, v64
	v_ashrrev_i32_e32 v133, 31, v132
	v_lshl_add_u64 v[126:127], v[126:127], 0, v[64:65]
	v_cvt_pk_bf16_f32 v125, v128, v129
	global_store_dwordx4 v[126:127], v[122:125], off sc1
	v_cvt_pk_bf16_f32 v118, v118, v119
	v_cvt_pk_bf16_f32 v119, v120, v121
	v_cvt_pk_bf16_f32 v120, v114, v115
	v_cvt_pk_bf16_f32 v121, v116, v117
	global_store_dwordx4 v[126:127], v[118:121], off offset:256 sc1
	v_cvt_pk_bf16_f32 v110, v110, v111
	v_cvt_pk_bf16_f32 v111, v112, v113
	v_cvt_pk_bf16_f32 v112, v106, v107
	v_lshlrev_b64 v[106:107], 11, v[132:133]
	v_or_b32_e32 v134, 32, v130
	v_lshl_add_u64 v[106:107], s[0:1], 0, v[106:107]
	v_ashrrev_i32_e32 v135, 31, v134
	v_lshl_add_u64 v[106:107], v[106:107], 0, v[64:65]
	v_cvt_pk_bf16_f32 v113, v108, v109
	global_store_dwordx4 v[106:107], v[110:113], off sc1
	v_cvt_pk_bf16_f32 v102, v102, v103
	v_cvt_pk_bf16_f32 v103, v104, v105
	v_cvt_pk_bf16_f32 v104, v98, v99
	v_cvt_pk_bf16_f32 v105, v100, v101
	global_store_dwordx4 v[106:107], v[102:105], off offset:256 sc1
	v_cvt_pk_bf16_f32 v94, v94, v95
	v_cvt_pk_bf16_f32 v95, v96, v97
	v_cvt_pk_bf16_f32 v96, v90, v91
	v_lshlrev_b64 v[90:91], 11, v[134:135]
	v_or_b32_e32 v136, 48, v130
	v_lshl_add_u64 v[90:91], s[0:1], 0, v[90:91]
	v_ashrrev_i32_e32 v137, 31, v136
	v_lshl_add_u64 v[90:91], v[90:91], 0, v[64:65]
	v_cvt_pk_bf16_f32 v97, v92, v93
	global_store_dwordx4 v[90:91], v[94:97], off sc1
	v_cvt_pk_bf16_f32 v86, v86, v87
	v_cvt_pk_bf16_f32 v87, v88, v89
	v_cvt_pk_bf16_f32 v88, v82, v83
	v_cvt_pk_bf16_f32 v89, v84, v85
	global_store_dwordx4 v[90:91], v[86:89], off offset:256 sc1
	v_cvt_pk_bf16_f32 v78, v78, v79
	v_cvt_pk_bf16_f32 v79, v80, v81
	v_cvt_pk_bf16_f32 v80, v74, v75
	v_lshlrev_b64 v[74:75], 11, v[136:137]
	v_lshl_add_u64 v[74:75], s[0:1], 0, v[74:75]
	v_lshl_add_u64 v[74:75], v[74:75], 0, v[64:65]
	s_mov_b32 s0, 0x40000
	v_cvt_pk_bf16_f32 v81, v76, v77
	global_store_dwordx4 v[74:75], v[78:81], off sc1
	v_cvt_pk_bf16_f32 v70, v70, v71
	v_cvt_pk_bf16_f32 v71, v72, v73
	v_cvt_pk_bf16_f32 v72, v66, v67
	v_cvt_pk_bf16_f32 v73, v68, v69
	global_store_dwordx4 v[74:75], v[70:73], off offset:256 sc1
	v_cvt_pk_bf16_f32 v60, v60, v61
	v_cvt_pk_bf16_f32 v61, v62, v63
	v_cvt_pk_bf16_f32 v62, v56, v57
	v_cvt_pk_bf16_f32 v63, v58, v59
	v_add_co_u32_e32 v58, vcc, s0, v126
	v_lshl_add_u64 v[56:57], v[126:127], 0, s[46:47]
	s_nop 0
	v_addc_co_u32_e32 v59, vcc, 0, v127, vcc
	s_mov_b32 s0, 0x48000
	global_store_dwordx4 v[58:59], v[60:63], off sc1
	v_cvt_pk_bf16_f32 v52, v52, v53
	v_cvt_pk_bf16_f32 v53, v54, v55
	v_cvt_pk_bf16_f32 v54, v48, v49
	v_cvt_pk_bf16_f32 v55, v50, v51
	global_store_dwordx4 v[56:57], v[52:55], off offset:256 sc1
	v_cvt_pk_bf16_f32 v44, v44, v45
	v_cvt_pk_bf16_f32 v45, v46, v47
	v_cvt_pk_bf16_f32 v46, v40, v41
	v_cvt_pk_bf16_f32 v47, v42, v43
	v_add_co_u32_e32 v42, vcc, s0, v126
	v_lshl_add_u64 v[40:41], v[126:127], 0, s[54:55]
	s_nop 0
	v_addc_co_u32_e32 v43, vcc, 0, v127, vcc
	s_mov_b32 s0, 0x50000
	global_store_dwordx4 v[42:43], v[44:47], off sc1
	v_cvt_pk_bf16_f32 v36, v36, v37
	v_cvt_pk_bf16_f32 v37, v38, v39
	v_cvt_pk_bf16_f32 v38, v32, v33
	v_cvt_pk_bf16_f32 v39, v34, v35
	global_store_dwordx4 v[40:41], v[36:39], off offset:256 sc1
	v_cvt_pk_bf16_f32 v28, v28, v29
	v_cvt_pk_bf16_f32 v29, v30, v31
	v_cvt_pk_bf16_f32 v30, v24, v25
	v_cvt_pk_bf16_f32 v31, v26, v27
	v_add_co_u32_e32 v26, vcc, s0, v126
	v_lshl_add_u64 v[24:25], v[126:127], 0, s[56:57]
	s_nop 0
	v_addc_co_u32_e32 v27, vcc, 0, v127, vcc
	s_mov_b32 s0, 0x58000
	global_store_dwordx4 v[26:27], v[28:31], off sc1
	v_cvt_pk_bf16_f32 v20, v20, v21
	v_cvt_pk_bf16_f32 v21, v22, v23
	v_cvt_pk_bf16_f32 v22, v16, v17
	v_cvt_pk_bf16_f32 v23, v18, v19
	global_store_dwordx4 v[24:25], v[20:23], off offset:256 sc1
	v_cvt_pk_bf16_f32 v12, v12, v13
	v_cvt_pk_bf16_f32 v13, v14, v15
	v_cvt_pk_bf16_f32 v14, v8, v9
	v_cvt_pk_bf16_f32 v15, v10, v11
	v_add_co_u32_e32 v10, vcc, s0, v126
	v_lshl_add_u64 v[8:9], v[126:127], 0, s[58:59]
	s_nop 0
	v_addc_co_u32_e32 v11, vcc, 0, v127, vcc
	global_store_dwordx4 v[10:11], v[12:15], off sc1
	v_cvt_pk_bf16_f32 v4, v4, v5
	v_cvt_pk_bf16_f32 v5, v6, v7
	v_cvt_pk_bf16_f32 v6, v0, v1
	v_cvt_pk_bf16_f32 v7, v2, v3
	global_store_dwordx4 v[8:9], v[4:7], off offset:256 sc1
	s_add_i32 s45, s45, s44
	s_waitcnt vmcnt(0)
	s_barrier
	s_waitcnt vmcnt(0)
	s_cmpk_gt_i32 s45, 0xff
	s_cselect_b64 s[0:1], -1, 0
	s_and_b64 vcc, exec, s[0:1]
	s_cbranch_vccnz .LBB0_1260
	s_waitcnt vmcnt(0) lgkmcnt(0)
	buffer_inv sc1
	s_branch .LBB0_1260
